# stacked de-serialisation edits on top of v49: residual epilogue counted waits (r_vm15), G3 state-fragment prefetch (g3_sbpre), pipelined attention merge (merge_pipe), G1 gate pre-activation on f32 MFM
# speedup vs baseline: 1.0041x; 1.0041x over previous
.LBB0_426:
	s_load_dwordx2 s[4:5], s[10:11], 0x70
	s_waitcnt vmcnt(0)
	v_bfe_u32 v51, v182, 4, 2
	v_mov_b64_e32 v[2:3], s[12:13]
	v_and_b32_e32 v50, 15, v182
	v_lshl_add_u32 v42, v51, 8, s31
	s_waitcnt lgkmcnt(0)
	s_add_u32 s24, s4, s28
	s_mul_hi_i32 s4, s30, 0x2aaaaaab
	s_addc_u32 s25, s5, 0
	s_lshr_b32 s5, s4, 31
	s_add_i32 s4, s4, s5
	s_add_i32 s26, s4, s36
	s_ashr_i32 s27, s26, 31
	s_lshl_b64 s[20:21], s[26:27], 6
	s_mul_i32 s5, s4, -6
	v_or_b32_e32 v4, s20, v51
	s_add_i32 s33, s30, s5
	s_mul_i32 s32, s26, 6
	s_add_i32 s32, s32, s33
	s_lshl_b32 s32, s32, 14
	s_add_u32 s46, s34, s32
	s_addc_u32 s47, s35, 0
	v_and_b32_e32 v212, 15, v182
	v_lshlrev_b32_e32 v212, 7, v212
	v_and_b32_e32 v213, 48, v182
	v_or_b32_e32 v212, v212, v213
	v_add_u32_e32 v213, 0x1000, v212
	v_add_u32_e32 v218, 0x2000, v212
	v_add_u32_e32 v219, 0x3000, v212
	global_load_dwordx4 v[198:201], v212, s[46:47]
	global_load_dwordx4 v[202:205], v212, s[46:47] offset:64
	global_load_dwordx4 v[206:209], v212, s[46:47] offset:2048
	global_load_dwordx4 v[220:223], v212, s[46:47] offset:2112
	global_load_dwordx4 v[224:227], v213, s[46:47]
	global_load_dwordx4 v[228:231], v213, s[46:47] offset:64
	global_load_dwordx4 v[236:239], v213, s[46:47] offset:2048
	global_load_dwordx4 v[248:251], v213, s[46:47] offset:2112
	v_mad_u64_u32 v[6:7], s[6:7], v4, s2, v[2:3]
	s_mul_i32 s5, s4, 0xfffffd00
	s_add_i32 s6, s37, s5
	s_ashr_i32 s7, s6, 31
	v_mad_i32_i24 v7, s21, v243, v7
	s_lshl_b64 s[22:23], s[6:7], 1
	v_lshl_add_u64 v[6:7], v[6:7], 0, s[22:23]
	v_lshlrev_b32_e32 v4, 4, v50
	v_lshl_add_u64 v[38:39], v[6:7], 0, v[4:5]
	v_lshlrev_b32_e32 v6, 4, v182
	v_and_b32_e32 v40, 16, v6
	v_add_co_u32_e32 v6, vcc, s75, v38
	s_mov_b32 s5, 0x39000
	s_nop 0
	v_addc_co_u32_e32 v7, vcc, 0, v39, vcc
	v_add_co_u32_e32 v10, vcc, s54, v38
	global_load_dwordx4 v[6:9], v[6:7], off
	s_nop 0
	v_addc_co_u32_e32 v11, vcc, 0, v39, vcc
	v_add_co_u32_e32 v14, vcc, s64, v38
	global_load_dwordx4 v[10:13], v[10:11], off
	s_nop 0
	v_addc_co_u32_e32 v15, vcc, 0, v39, vcc
	v_add_co_u32_e32 v18, vcc, s41, v38
	global_load_dwordx4 v[14:17], v[14:15], off
	s_nop 0
	v_addc_co_u32_e32 v19, vcc, 0, v39, vcc
	v_add_co_u32_e32 v22, vcc, s57, v38
	global_load_dwordx4 v[18:21], v[18:19], off
	s_nop 0
	v_addc_co_u32_e32 v23, vcc, 0, v39, vcc
	v_add_co_u32_e32 v26, vcc, s5, v38
	global_load_dwordx4 v[22:25], v[22:23], off
	s_nop 0
	v_addc_co_u32_e32 v27, vcc, 0, v39, vcc
	v_add_co_u32_e32 v30, vcc, s58, v38
	s_mov_b32 s5, 0x4f000
	s_nop 0
	v_addc_co_u32_e32 v31, vcc, 0, v39, vcc
	global_load_dwordx4 v[26:29], v[26:27], off
	v_add_co_u32_e32 v34, vcc, s5, v38
	global_load_dwordx4 v[30:33], v[30:31], off
	s_nop 0
	v_addc_co_u32_e32 v35, vcc, 0, v39, vcc
	global_load_dwordx4 v[34:37], v[34:35], off
	v_bfe_u32 v4, v182, 1, 3
	v_xor_b32_e32 v43, v51, v4
	v_lshlrev_b32_e32 v43, 5, v43
	v_or_b32_e32 v41, 4, v51
	v_add3_u32 v43, v42, v43, v40
	v_bitop3_b32 v4, v51, v4, 4 bitop3:0x36
	v_lshlrev_b32_e32 v4, 5, v4
	s_mov_b32 s5, 0x65000
	s_mulk_i32 s4, 0xfe80
	v_or_b32_e32 v178, s20, v50
	s_add_i32 s4, s38, s4
	v_lshlrev_b32_e32 v184, 2, v51
	v_sub_u32_e32 v51, v50, v184
	v_cmp_lt_i32_e64 s[8:9], 2, v51
	v_mov_b32_e32 v132, v5
	v_mov_b32_e32 v133, v5
	v_mov_b32_e32 v80, v5
	v_mov_b32_e32 v81, v5
	v_mov_b32_e32 v179, s21
	v_and_b32_e32 v183, 63, v182
	s_waitcnt vmcnt(7)
	ds_write_b128 v43, v[6:9]
	v_lshl_add_u32 v6, v41, 8, s31
	v_add3_u32 v6, v6, v4, v40
	s_waitcnt vmcnt(6)
	ds_write_b128 v6, v[10:13]
	s_waitcnt vmcnt(5)
	ds_write_b128 v43, v[14:17] offset:2048
	v_add_co_u32_e32 v6, vcc, s59, v38
	v_add3_u32 v4, v42, v4, v40
	s_nop 0
	v_addc_co_u32_e32 v7, vcc, 0, v39, vcc
	v_add_co_u32_e32 v10, vcc, s5, v38
	s_mov_b32 s5, 0x7b000
	s_nop 0
	v_addc_co_u32_e32 v11, vcc, 0, v39, vcc
	v_add_co_u32_e32 v14, vcc, s60, v38
	s_waitcnt vmcnt(4)
	ds_write_b128 v4, v[18:21] offset:3072
	s_waitcnt vmcnt(3)
	ds_write_b128 v43, v[22:25] offset:4096
	s_waitcnt vmcnt(2)
	ds_write_b128 v4, v[26:29] offset:5120
	s_waitcnt vmcnt(1)
	ds_write_b128 v43, v[30:33] offset:6144
	s_waitcnt vmcnt(0)
	ds_write_b128 v4, v[34:37] offset:7168
	v_addc_co_u32_e32 v15, vcc, 0, v39, vcc
	v_add_co_u32_e32 v18, vcc, s5, v38
	global_load_dwordx4 v[6:9], v[6:7], off
	s_nop 0
	v_addc_co_u32_e32 v19, vcc, 0, v39, vcc
	v_add_co_u32_e32 v22, vcc, s97, v38
	s_mov_b32 s5, 0x91000
	s_nop 0
	v_addc_co_u32_e32 v23, vcc, 0, v39, vcc
	global_load_dwordx4 v[10:13], v[10:11], off
	v_add_co_u32_e32 v26, vcc, s5, v38
	global_load_dwordx4 v[14:17], v[14:15], off
	s_nop 0
	v_addc_co_u32_e32 v27, vcc, 0, v39, vcc
	global_load_dwordx4 v[18:21], v[18:19], off
	v_add_co_u32_e32 v30, vcc, s39, v38
	global_load_dwordx4 v[22:25], v[22:23], off
	s_nop 0
	v_addc_co_u32_e32 v31, vcc, 0, v39, vcc
	s_mov_b32 s5, 0xa7000
	global_load_dwordx4 v[26:29], v[26:27], off
	v_add_co_u32_e32 v34, vcc, s5, v38
	global_load_dwordx4 v[30:33], v[30:31], off
	s_nop 0
	v_addc_co_u32_e32 v35, vcc, 0, v39, vcc
	global_load_dwordx4 v[34:37], v[34:35], off
	s_ashr_i32 s5, s4, 31
	s_lshl_b64 s[4:5], s[4:5], 1
	s_waitcnt vmcnt(7)
	ds_write_b128 v43, v[6:9] offset:8192
	s_waitcnt vmcnt(6)
	ds_write_b128 v4, v[10:13] offset:9216
	s_waitcnt vmcnt(5)
	ds_write_b128 v43, v[14:17] offset:10240
	s_waitcnt vmcnt(4)
	ds_write_b128 v4, v[18:21] offset:11264
	s_waitcnt vmcnt(3)
	ds_write_b128 v43, v[22:25] offset:12288
	s_waitcnt vmcnt(2)
	ds_write_b128 v4, v[26:29] offset:13312
	s_waitcnt vmcnt(1)
	ds_write_b128 v43, v[30:33] offset:14336
	s_waitcnt vmcnt(0)
	ds_write_b128 v4, v[34:37] offset:15360
	v_mov_b64_e32 v[6:7], s[14:15]
	v_mad_u64_u32 v[6:7], s[6:7], v178, s66, v[6:7]
	v_mad_i32_i24 v7, s21, v247, v7
	v_lshl_add_u64 v[6:7], v[6:7], 0, s[4:5]
	v_and_b32_e32 v4, 48, v182
	v_lshl_add_u64 v[42:43], v[6:7], 0, v[4:5]
	v_mov_b64_e32 v[6:7], s[16:17]
	v_mad_u64_u32 v[6:7], s[6:7], v178, s66, v[6:7]
	v_mad_i32_i24 v7, s21, v247, v7
	v_lshl_add_u64 v[6:7], v[6:7], 0, s[4:5]
	v_lshl_add_u64 v[44:45], v[6:7], 0, v[4:5]
	global_load_dwordx4 v[14:17], v[42:43], off
	global_load_dwordx4 v[6:9], v[44:45], off
	global_load_dwordx4 v[10:13], v[42:43], off offset:64
	global_load_dwordx4 v[22:25], v[44:45], off offset:64
	v_add_co_u32_e32 v18, vcc, s74, v42
	v_cmp_lt_i32_e64 s[6:7], 1, v51
	s_nop 0
	v_addc_co_u32_e32 v19, vcc, 0, v43, vcc
	global_load_dwordx4 v[54:57], v[18:19], off
	v_add_co_u32_e32 v30, vcc, s74, v44
	v_cmp_lt_i32_e64 s[4:5], 0, v51
	s_nop 0
	v_addc_co_u32_e32 v31, vcc, 0, v45, vcc
	global_load_dwordx4 v[26:29], v[30:31], off
	s_nop 0
	global_load_dwordx4 v[18:21], v[18:19], off offset:64
	s_nop 0
	global_load_dwordx4 v[30:33], v[30:31], off offset:64
	v_add_co_u32_e32 v38, vcc, s62, v42
	s_waitcnt vmcnt(6)
	v_mfma_f32_16x16x32_bf16 v[62:65], v[6:9], v[14:17], 0
	v_addc_co_u32_e32 v39, vcc, 0, v43, vcc
	v_add_co_u32_e32 v40, vcc, s62, v44
	global_load_dwordx4 v[66:69], v[38:39], off
	s_nop 0
	v_addc_co_u32_e32 v41, vcc, 0, v45, vcc
	v_add_co_u32_e32 v46, vcc, s93, v42
	global_load_dwordx4 v[34:37], v[40:41], off
	global_load_dwordx4 v[58:61], v[38:39], off offset:64
	s_nop 0
	global_load_dwordx4 v[38:41], v[40:41], off offset:64
	v_addc_co_u32_e32 v47, vcc, 0, v43, vcc
	global_load_dwordx4 v[74:77], v[46:47], off
	v_add_co_u32_e32 v48, vcc, s93, v44
	s_waitcnt vmcnt(9)
	v_mfma_f32_16x16x32_bf16 v[62:65], v[22:25], v[10:13], v[62:65]
	v_addc_co_u32_e32 v49, vcc, 0, v45, vcc
	global_load_dwordx4 v[42:45], v[48:49], off
	global_load_dwordx4 v[70:73], v[46:47], off offset:64
	s_nop 0
	global_load_dwordx4 v[46:49], v[48:49], off offset:64
	v_cmp_lt_i32_e32 vcc, -1, v51
	s_nop 1
	v_cndmask_b32_e64 v53, 0, v64, s[6:7]
	v_cndmask_b32_e64 v52, 0, v63, s[4:5]
	v_cndmask_b32_e32 v51, 0, v62, vcc
	v_cndmask_b32_e64 v62, 0, v65, s[8:9]
	v_cvt_pk_bf16_f32 v131, v53, v62
	s_waitcnt vmcnt(11)
	v_mfma_f32_16x16x32_bf16 v[62:65], v[6:9], v[54:57], 0
	v_cvt_pk_bf16_f32 v130, v51, v52
	s_waitcnt lgkmcnt(0)
	s_waitcnt vmcnt(9)
	v_mfma_f32_16x16x32_bf16 v[62:65], v[22:25], v[18:21], v[62:65]
	s_nop 7
	v_cvt_pk_bf16_f32 v142, v62, v63
	v_cvt_pk_bf16_f32 v143, v64, v65
	v_mfma_f32_16x16x32_bf16 v[62:65], v[26:29], v[54:57], 0
	s_waitcnt vmcnt(8)
	v_mfma_f32_16x16x32_bf16 v[62:65], v[30:33], v[18:21], v[62:65]
	s_nop 7
	v_cndmask_b32_e32 v51, 0, v62, vcc
	v_cndmask_b32_e64 v53, 0, v64, s[6:7]
	v_cndmask_b32_e64 v62, 0, v65, s[8:9]
	v_cndmask_b32_e64 v52, 0, v63, s[4:5]
	v_cvt_pk_bf16_f32 v145, v53, v62
	s_waitcnt vmcnt(7)
	v_mfma_f32_16x16x32_bf16 v[62:65], v[6:9], v[66:69], 0
	v_cvt_pk_bf16_f32 v144, v51, v52
	s_waitcnt vmcnt(3)
	v_mfma_f32_16x16x32_bf16 v[6:9], v[6:9], v[74:77], 0
	s_waitcnt vmcnt(1)
	v_mfma_f32_16x16x32_bf16 v[6:9], v[22:25], v[70:73], v[6:9]
	v_mfma_f32_16x16x32_bf16 v[62:65], v[22:25], v[58:61], v[62:65]
	s_nop 6
	v_cvt_pk_bf16_f32 v154, v6, v7
	v_cvt_pk_bf16_f32 v155, v8, v9
	v_mfma_f32_16x16x32_bf16 v[6:9], v[26:29], v[74:77], 0
	v_mfma_f32_16x16x32_bf16 v[6:9], v[30:33], v[70:73], v[6:9]
	v_cvt_pk_bf16_f32 v146, v62, v63
	v_cvt_pk_bf16_f32 v147, v64, v65
	v_mfma_f32_16x16x32_bf16 v[62:65], v[26:29], v[66:69], 0
	v_mfma_f32_16x16x32_bf16 v[62:65], v[30:33], v[58:61], v[62:65]
	s_nop 3
	v_cvt_pk_bf16_f32 v156, v6, v7
	v_cvt_pk_bf16_f32 v157, v8, v9
	v_mfma_f32_16x16x32_bf16 v[6:9], v[34:37], v[74:77], 0
	v_mfma_f32_16x16x32_bf16 v[6:9], v[38:41], v[70:73], v[6:9]
	v_cvt_pk_bf16_f32 v148, v62, v63
	v_cvt_pk_bf16_f32 v149, v64, v65
	v_mfma_f32_16x16x32_bf16 v[62:65], v[34:37], v[66:69], 0
	v_mfma_f32_16x16x32_bf16 v[62:65], v[38:41], v[58:61], v[62:65]
	s_nop 3
	v_cvt_pk_bf16_f32 v98, v6, v7
	v_cvt_pk_bf16_f32 v99, v8, v9
	v_mfma_f32_16x16x32_bf16 v[6:9], v[42:45], v[74:77], 0
	s_waitcnt vmcnt(0)
	v_mfma_f32_16x16x32_bf16 v[6:9], v[46:49], v[70:73], v[6:9]
	v_cndmask_b32_e64 v52, 0, v63, s[4:5]
	v_cndmask_b32_e64 v53, 0, v64, s[6:7]
	v_cndmask_b32_e32 v51, 0, v62, vcc
	v_cndmask_b32_e64 v62, 0, v65, s[8:9]
	v_cvt_pk_bf16_f32 v78, v51, v52
	s_nop 2
	v_cndmask_b32_e32 v6, 0, v6, vcc
	v_cndmask_b32_e64 v7, 0, v7, s[4:5]
	v_cndmask_b32_e64 v8, 0, v8, s[6:7]
	v_cndmask_b32_e64 v9, 0, v9, s[8:9]
	v_cvt_pk_bf16_f32 v100, v6, v7
	v_bfe_u32 v6, v182, 2, 2
	v_cvt_pk_bf16_f32 v101, v8, v9
	v_and_or_b32 v7, v184, 4, v6
	v_or_b32_e32 v6, v184, v6
	v_lshlrev_b32_e32 v8, 3, v182
	v_lshlrev_b32_e32 v6, 8, v6
	v_and_b32_e32 v8, 24, v8
	v_add3_u32 v174, s31, v6, v8
	v_lshlrev_b32_e32 v175, 5, v7
	v_add_u32_e32 v36, v174, v175
	ds_read_b64_tr_b16 v[6:7], v36
	ds_read_b64_tr_b16 v[8:9], v36 offset:4096
	s_mul_i32 s4, s26, 6
	s_ashr_i32 s6, s33, 31
	s_mul_hi_i32 s5, s26, 6
	s_add_u32 s4, s4, s33
	ds_read_b64_tr_b16 v[34:35], v36 offset:8192
	ds_read_b64_tr_b16 v[36:37], v36 offset:12288
	s_addc_u32 s5, s5, s6
	s_waitcnt lgkmcnt(2)
	v_mfma_f32_16x16x32_bf16 v[22:25], v[6:9], v[130:133], 0
	s_lshl_b64 s[4:5], s[4:5], 14
	s_add_u32 s4, s34, s4
	v_cvt_pk_bf16_f32 v79, v53, v62
	v_mfma_f32_16x16x32_bf16 v[26:29], v[6:9], v[142:145], 0
	s_addc_u32 s5, s35, s5
	v_lshl_add_u64 v[38:39], s[4:5], 0, v[4:5]
	v_xad_u32 v88, v175, s63, v174
	v_mfma_f32_16x16x32_bf16 v[30:33], v[6:9], v[146:149], 0
	v_xad_u32 v96, v175, s48, v174
	s_movk_i32 s4, 0xa0
	v_xad_u32 v128, v175, s4, v174
	v_mfma_f32_16x16x32_bf16 v[6:9], v[6:9], v[154:157], 0
	s_movk_i32 s4, 0xc0
	s_addk_i32 s37, 0x400
	s_addk_i32 s38, 0x200
	s_waitcnt lgkmcnt(0)
	v_mfma_f32_16x16x32_bf16 v[30:33], v[34:37], v[78:81], v[30:33]
	v_mfma_f32_16x16x32_bf16 v[34:37], v[34:37], v[98:101], v[6:9]
	s_nop 2
	v_lshlrev_b32_e32 v6, 7, v50
	v_mov_b32_e32 v7, v5
	v_lshl_add_u64 v[6:7], v[38:39], 0, v[6:7]
	v_mfma_f32_16x16x32_bf16 v[22:25], v[198:201], v[14:17], v[22:25]
	v_xad_u32 v8, v175, 32, v174
	v_add_co_u32_e32 v90, vcc, s1, v6
	v_mfma_f32_16x16x32_bf16 v[26:29], v[198:201], v[54:57], v[26:29]
	s_nop 0
	v_addc_co_u32_e32 v91, vcc, 0, v7, vcc
	v_mfma_f32_16x16x32_bf16 v[30:33], v[198:201], v[66:69], v[30:33]
	v_mfma_f32_16x16x32_bf16 v[34:37], v[198:201], v[74:77], v[34:37]
	global_load_dwordx4 v[198:201], v218, s[46:47]
	v_mfma_f32_16x16x32_bf16 v[102:105], v[202:205], v[18:21], v[26:29]
	s_nop 2
	ds_read_b64_tr_b16 v[26:27], v8
	ds_read_b64_tr_b16 v[28:29], v8 offset:4096
	ds_read_b64_tr_b16 v[42:43], v8 offset:8192
	ds_read_b64_tr_b16 v[44:45], v8 offset:12288
	v_xad_u32 v8, v175, 64, v174
	v_mfma_f32_16x16x32_bf16 v[134:137], v[202:205], v[10:13], v[22:25]
	v_mov_b32_e32 v214, v103
	v_mov_b32_e32 v216, v105
	v_mfma_f32_16x16x32_bf16 v[46:49], v[202:205], v[58:61], v[30:33]
	v_mfma_f32_16x16x32_bf16 v[22:25], v[202:205], v[70:73], v[34:37]
	global_load_dwordx4 v[202:205], v218, s[46:47] offset:64
	s_waitcnt lgkmcnt(2)
	v_mfma_f32_16x16x32_bf16 v[30:33], v[26:29], v[130:133], 0
	v_mfma_f32_16x16x32_bf16 v[34:37], v[26:29], v[142:145], 0
	v_mfma_f32_16x16x32_bf16 v[38:41], v[26:29], v[146:149], 0
	v_mfma_f32_16x16x32_bf16 v[26:29], v[26:29], v[154:157], 0
	s_waitcnt lgkmcnt(0)
	v_mfma_f32_16x16x32_bf16 v[38:41], v[42:45], v[78:81], v[38:41]
	v_mfma_f32_16x16x32_bf16 v[26:29], v[42:45], v[98:101], v[26:29]
	v_mfma_f32_16x16x32_bf16 v[30:33], v[206:209], v[14:17], v[30:33]
	v_mfma_f32_16x16x32_bf16 v[34:37], v[206:209], v[54:57], v[34:37]
	v_mfma_f32_16x16x32_bf16 v[38:41], v[206:209], v[66:69], v[38:41]
	v_mfma_f32_16x16x32_bf16 v[26:29], v[206:209], v[74:77], v[26:29]
	global_load_dwordx4 v[206:209], v218, s[46:47] offset:2048
	v_mfma_f32_16x16x32_bf16 v[138:141], v[220:223], v[10:13], v[30:33]
	s_nop 2
	ds_read_b64_tr_b16 v[30:31], v8
	ds_read_b64_tr_b16 v[32:33], v8 offset:4096
	ds_read_b64_tr_b16 v[62:63], v8 offset:8192
	ds_read_b64_tr_b16 v[64:65], v8 offset:12288
	v_add_co_u32_e32 v8, vcc, s75, v6
	v_mfma_f32_16x16x32_bf16 v[106:109], v[220:223], v[18:21], v[34:37]
	s_nop 0
	v_addc_co_u32_e32 v9, vcc, 0, v7, vcc
	v_mfma_f32_16x16x32_bf16 v[50:53], v[220:223], v[58:61], v[38:41]
	v_add_co_u32_e32 v180, vcc, s74, v6
	s_nop 2
	v_mov_b32_e32 v215, v107
	v_mfma_f32_16x16x32_bf16 v[26:29], v[220:223], v[70:73], v[26:29]
	global_load_dwordx4 v[220:223], v218, s[46:47] offset:2112
	v_addc_co_u32_e32 v181, vcc, 0, v7, vcc
	v_cmp_lt_i32_e32 vcc, v1, v234
	s_waitcnt lgkmcnt(2)
	v_mfma_f32_16x16x32_bf16 v[34:37], v[30:33], v[130:133], 0
	v_mul_f32_e64 v214, v214, v214
	v_mul_f32_e64 v215, v215, v215
	v_mov_b32_e32 v217, v109
	v_pk_mul_f32 v[216:217], v[216:217], v[216:217]
	v_mfma_f32_16x16x32_bf16 v[38:41], v[30:33], v[142:145], 0
	v_mfma_f32_16x16x32_bf16 v[42:45], v[30:33], v[146:149], 0
	v_mfma_f32_16x16x32_bf16 v[30:33], v[30:33], v[154:157], 0
	s_waitcnt lgkmcnt(0)
	v_mfma_f32_16x16x32_bf16 v[42:45], v[62:65], v[78:81], v[42:45]
	v_mfma_f32_16x16x32_bf16 v[30:33], v[62:65], v[98:101], v[30:33]
	v_mfma_f32_16x16x32_bf16 v[34:37], v[224:227], v[14:17], v[34:37]
	v_mfma_f32_16x16x32_bf16 v[150:153], v[228:231], v[10:13], v[34:37]
	s_nop 6
	ds_read_b64_tr_b16 v[34:35], v88
	ds_read_b64_tr_b16 v[36:37], v88 offset:4096
	ds_read_b64_tr_b16 v[86:87], v88 offset:8192
	ds_read_b64_tr_b16 v[88:89], v88 offset:12288
	v_mfma_f32_16x16x32_bf16 v[38:41], v[224:227], v[54:57], v[38:41]
	v_mfma_f32_16x16x32_bf16 v[42:45], v[224:227], v[66:69], v[42:45]
	v_mfma_f32_16x16x32_bf16 v[30:33], v[224:227], v[74:77], v[30:33]
	global_load_dwordx4 v[224:227], v219, s[46:47]
	v_mfma_f32_16x16x32_bf16 v[110:113], v[228:231], v[18:21], v[38:41]
	v_mfma_f32_16x16x32_bf16 v[62:65], v[228:231], v[58:61], v[42:45]
	v_mfma_f32_16x16x32_bf16 v[30:33], v[228:231], v[70:73], v[30:33]
	global_load_dwordx4 v[228:231], v219, s[46:47] offset:64
	s_waitcnt lgkmcnt(2)
	v_mfma_f32_16x16x32_bf16 v[38:41], v[34:37], v[130:133], 0
	v_mfma_f32_16x16x32_bf16 v[42:45], v[34:37], v[142:145], 0
	v_mfma_f32_16x16x32_bf16 v[82:85], v[34:37], v[146:149], 0
	v_mfma_f32_16x16x32_bf16 v[34:37], v[34:37], v[154:157], 0
	s_waitcnt lgkmcnt(0)
	v_mfma_f32_16x16x32_bf16 v[82:85], v[86:89], v[78:81], v[82:85]
	v_mfma_f32_16x16x32_bf16 v[34:37], v[86:89], v[98:101], v[34:37]
	v_mfma_f32_16x16x32_bf16 v[38:41], v[236:239], v[14:17], v[38:41]
	v_mfma_f32_16x16x32_bf16 v[42:45], v[236:239], v[54:57], v[42:45]
	v_mfma_f32_16x16x32_bf16 v[82:85], v[236:239], v[66:69], v[82:85]
	v_mfma_f32_16x16x32_bf16 v[34:37], v[236:239], v[74:77], v[34:37]
	global_load_dwordx4 v[236:239], v219, s[46:47] offset:2048
	v_mfma_f32_16x16x32_bf16 v[158:161], v[248:251], v[10:13], v[38:41]
	s_nop 2
	ds_read_b64_tr_b16 v[38:39], v96
	ds_read_b64_tr_b16 v[40:41], v96 offset:4096
	ds_read_b64_tr_b16 v[94:95], v96 offset:8192
	ds_read_b64_tr_b16 v[96:97], v96 offset:12288
	v_mfma_f32_16x16x32_bf16 v[114:117], v[248:251], v[18:21], v[42:45]
	v_mfma_f32_16x16x32_bf16 v[82:85], v[248:251], v[58:61], v[82:85]
	v_mfma_f32_16x16x32_bf16 v[34:37], v[248:251], v[70:73], v[34:37]
	global_load_dwordx4 v[248:251], v219, s[46:47] offset:2112
	s_waitcnt lgkmcnt(2)
	v_mfma_f32_16x16x32_bf16 v[42:45], v[38:41], v[130:133], 0
	v_mfma_f32_16x16x32_bf16 v[86:89], v[38:41], v[142:145], 0
	v_mfma_f32_16x16x32_bf16 v[90:93], v[38:41], v[146:149], 0
	v_mfma_f32_16x16x32_bf16 v[38:41], v[38:41], v[154:157], 0
	s_waitcnt lgkmcnt(0)
	v_mfma_f32_16x16x32_bf16 v[90:93], v[94:97], v[78:81], v[90:93]
	v_mfma_f32_16x16x32_bf16 v[38:41], v[94:97], v[98:101], v[38:41]
	s_waitcnt vmcnt(7)
	v_mfma_f32_16x16x32_bf16 v[42:45], v[198:201], v[14:17], v[42:45]
	v_mfma_f32_16x16x32_bf16 v[86:89], v[198:201], v[54:57], v[86:89]
	v_mfma_f32_16x16x32_bf16 v[90:93], v[198:201], v[66:69], v[90:93]
	v_mfma_f32_16x16x32_bf16 v[38:41], v[198:201], v[74:77], v[38:41]
	s_waitcnt vmcnt(6)
	v_mfma_f32_16x16x32_bf16 v[162:165], v[202:205], v[10:13], v[42:45]
	s_nop 2
	ds_read_b64_tr_b16 v[42:43], v128
	ds_read_b64_tr_b16 v[44:45], v128 offset:4096
	ds_read_b64_tr_b16 v[126:127], v128 offset:8192
	ds_read_b64_tr_b16 v[128:129], v128 offset:12288
	v_mfma_f32_16x16x32_bf16 v[118:121], v[202:205], v[18:21], v[86:89]
	v_mfma_f32_16x16x32_bf16 v[86:89], v[202:205], v[58:61], v[90:93]
	v_mfma_f32_16x16x32_bf16 v[38:41], v[202:205], v[70:73], v[38:41]
	s_waitcnt lgkmcnt(2)
	v_mfma_f32_16x16x32_bf16 v[90:93], v[42:45], v[130:133], 0
	v_mfma_f32_16x16x32_bf16 v[94:97], v[42:45], v[142:145], 0
	v_mfma_f32_16x16x32_bf16 v[122:125], v[42:45], v[146:149], 0
	v_mfma_f32_16x16x32_bf16 v[42:45], v[42:45], v[154:157], 0
	s_waitcnt lgkmcnt(0)
	v_mfma_f32_16x16x32_bf16 v[122:125], v[126:129], v[78:81], v[122:125]
	v_mfma_f32_16x16x32_bf16 v[42:45], v[126:129], v[98:101], v[42:45]
	s_waitcnt vmcnt(5)
	v_mfma_f32_16x16x32_bf16 v[90:93], v[206:209], v[14:17], v[90:93]
	v_mfma_f32_16x16x32_bf16 v[94:97], v[206:209], v[54:57], v[94:97]
	v_mfma_f32_16x16x32_bf16 v[170:173], v[206:209], v[66:69], v[122:125]
	v_mfma_f32_16x16x32_bf16 v[42:45], v[206:209], v[74:77], v[42:45]
	v_xad_u32 v8, v175, s4, v174
	s_movk_i32 s4, 0xe0
	s_waitcnt vmcnt(4)
	v_mfma_f32_16x16x32_bf16 v[122:125], v[220:223], v[18:21], v[94:97]
	s_nop 2
	ds_read_b64_tr_b16 v[94:95], v8
	ds_read_b64_tr_b16 v[96:97], v8 offset:4096
	ds_read_b64_tr_b16 v[190:191], v8 offset:8192
	ds_read_b64_tr_b16 v[192:193], v8 offset:12288
	s_waitcnt lgkmcnt(2)
	v_mfma_f32_16x16x32_bf16 v[186:189], v[94:97], v[146:149], 0
	v_xad_u32 v185, v175, s4, v174
	v_mfma_f32_16x16x32_bf16 v[166:169], v[220:223], v[10:13], v[90:93]
	v_mfma_f32_16x16x32_bf16 v[90:93], v[220:223], v[58:61], v[170:173]
	v_mfma_f32_16x16x32_bf16 v[42:45], v[220:223], v[70:73], v[42:45]
	v_mfma_f32_16x16x32_bf16 v[126:129], v[94:97], v[130:133], 0
	v_mfma_f32_16x16x32_bf16 v[170:173], v[94:97], v[142:145], 0
	v_mfma_f32_16x16x32_bf16 v[94:97], v[94:97], v[154:157], 0
	s_waitcnt lgkmcnt(0)
	v_mfma_f32_16x16x32_bf16 v[186:189], v[190:193], v[78:81], v[186:189]
	v_mfma_f32_16x16x32_bf16 v[94:97], v[190:193], v[98:101], v[94:97]
	s_waitcnt vmcnt(3)
	v_mfma_f32_16x16x32_bf16 v[186:189], v[224:227], v[66:69], v[186:189]
	v_mfma_f32_16x16x32_bf16 v[126:129], v[224:227], v[14:17], v[126:129]
	v_mfma_f32_16x16x32_bf16 v[190:193], v[224:227], v[54:57], v[170:173]
	v_mfma_f32_16x16x32_bf16 v[6:9], v[224:227], v[74:77], v[94:97]
	s_waitcnt vmcnt(2)
	v_mfma_f32_16x16x32_bf16 v[94:97], v[228:231], v[58:61], v[186:189]
	s_nop 2
	ds_read_b64_tr_b16 v[186:187], v185
	ds_read_b64_tr_b16 v[188:189], v185 offset:4096
	s_waitcnt lgkmcnt(0)
	v_mfma_f32_16x16x32_bf16 v[174:177], v[186:189], v[146:149], 0
	v_mfma_f32_16x16x32_bf16 v[146:149], v[186:189], v[154:157], 0
	ds_read_b64_tr_b16 v[154:155], v185 offset:8192
	ds_read_b64_tr_b16 v[156:157], v185 offset:12288
	s_waitcnt lgkmcnt(0)
	v_mfma_f32_16x16x32_bf16 v[98:101], v[154:157], v[98:101], v[146:149]
	s_nop 3
	v_mfma_f32_16x16x32_bf16 v[78:81], v[154:157], v[78:81], v[174:177]
	s_waitcnt vmcnt(1)
	v_mfma_f32_16x16x32_bf16 v[66:69], v[236:239], v[66:69], v[78:81]
	s_nop 5
	v_mfma_f32_16x16x32_bf16 v[130:133], v[186:189], v[130:133], 0
	v_mfma_f32_16x16x32_bf16 v[142:145], v[186:189], v[142:145], 0
	v_mfma_f32_16x16x32_bf16 v[14:17], v[236:239], v[14:17], v[130:133]
	v_mfma_f32_16x16x32_bf16 v[54:57], v[236:239], v[54:57], v[142:145]
	s_waitcnt vmcnt(0)
	v_mfma_f32_16x16x32_bf16 v[142:145], v[248:251], v[10:13], v[14:17]
	s_nop 4
	v_cndmask_b32_e32 v14, v233, v1, vcc
	v_cmp_lt_i32_e32 vcc, v240, v234
	v_lshlrev_b32_e32 v176, 2, v14
	v_mov_b32_e32 v16, v135
	v_cndmask_b32_e32 v14, v233, v240, vcc
	v_lshlrev_b32_e32 v177, 2, v14
	v_and_b32_e32 v14, 16, v182
	v_cmp_eq_u32_e32 vcc, 0, v14
	v_add_u32_e32 v14, 12, v184
	v_mov_b32_e32 v17, v139
	v_mfma_f32_16x16x32_bf16 v[170:173], v[228:231], v[10:13], v[126:129]
	v_mov_b32_e32 v15, v138
	v_pk_mul_f32 v[16:17], v[16:17], v[16:17]
	v_mfma_f32_16x16x32_bf16 v[126:129], v[228:231], v[18:21], v[190:193]
	v_mfma_f32_16x16x32_bf16 v[130:133], v[248:251], v[18:21], v[54:57]
	v_mov_b32_e32 v18, v137
	v_mov_b32_e32 v19, v141
	v_pk_mul_f32 v[18:19], v[18:19], v[18:19]
	v_cndmask_b32_e32 v54, v14, v184, vcc
	v_mov_b32_e32 v14, v134
	v_pk_fma_f32 v[14:15], v[14:15], v[14:15], v[16:17]
	v_mov_b32_e32 v16, v136
	v_mov_b32_e32 v17, v140
	v_pk_fma_f32 v[16:17], v[16:17], v[16:17], v[18:19]
	v_pk_mul_f32 v[18:19], v[150:151], v[150:151]
	v_pk_add_f32 v[14:15], v[14:15], v[16:17]
	v_pk_mul_f32 v[16:17], v[152:153], v[152:153]
	v_pk_add_f32 v[14:15], v[14:15], v[14:15] op_sel:[0,1] op_sel_hi:[1,0]
	v_pk_mov_b32 v[20:21], v[18:19], v[16:17] op_sel:[1,0]
	v_mov_b32_e32 v19, v17
	v_pk_add_f32 v[16:17], v[20:21], v[18:19]
	v_mul_f32_e32 v18, v162, v162
	v_mul_f32_e32 v19, v163, v163
	v_pk_add_f32 v[16:17], v[16:17], v[16:17] op_sel:[0,1] op_sel_hi:[1,0]
	v_mov_b32_e32 v15, v18
	v_mov_b32_e32 v17, v19
	v_pk_add_f32 v[14:15], v[14:15], v[16:17]
	v_mul_f32_e32 v16, v159, v159
	v_mul_f32_e32 v18, v161, v161
	v_mul_f32_e32 v20, v164, v164
	v_mul_f32_e32 v21, v165, v165
	v_pk_fma_f32 v[16:17], v[158:159], v[158:159], v[16:17] op_sel_hi:[1,1,0]
	v_pk_fma_f32 v[18:19], v[160:161], v[160:161], v[18:19] op_sel_hi:[1,1,0]
	v_mov_b32_e32 v17, v20
	v_mov_b32_e32 v19, v21
	v_pk_add_f32 v[16:17], v[16:17], v[18:19]
	v_pk_mul_f32 v[18:19], v[166:167], v[166:167]
	v_pk_add_f32 v[14:15], v[14:15], v[16:17]
	v_pk_mul_f32 v[16:17], v[168:169], v[168:169]
	v_pk_add_f32 v[14:15], v[14:15], v[14:15] op_sel:[0,1] op_sel_hi:[1,0]
	v_pk_mov_b32 v[20:21], v[18:19], v[16:17] op_sel:[1,0]
	v_mov_b32_e32 v19, v17
	v_pk_add_f32 v[16:17], v[20:21], v[18:19]
	v_mul_f32_e32 v18, v142, v142
	v_mul_f32_e32 v19, v143, v143
	v_pk_add_f32 v[16:17], v[16:17], v[16:17] op_sel:[0,1] op_sel_hi:[1,0]
	v_mov_b32_e32 v15, v18
	v_mov_b32_e32 v17, v19
	v_pk_add_f32 v[14:15], v[14:15], v[16:17]
	v_mul_f32_e32 v16, v171, v171
	v_mul_f32_e32 v18, v173, v173
	v_mul_f32_e32 v20, v144, v144
	v_mul_f32_e32 v21, v145, v145
	v_pk_fma_f32 v[16:17], v[170:171], v[170:171], v[16:17] op_sel_hi:[1,1,0]
	v_pk_fma_f32 v[18:19], v[172:173], v[172:173], v[18:19] op_sel_hi:[1,1,0]
	v_mov_b32_e32 v17, v20
	v_mov_b32_e32 v19, v21
	v_pk_add_f32 v[16:17], v[16:17], v[18:19]
	v_mfma_f32_16x16x32_bf16 v[74:77], v[236:239], v[74:77], v[98:101]
	v_add_f32_e64 v148, v14, v16
	v_add_f32_e64 v149, v15, v17
	v_mad_u64_u32 v[14:15], s[4:5], v178, s2, v[2:3]
	v_mad_i32_i24 v15, s21, v243, v15
	v_lshl_add_u64 v[14:15], v[14:15], 0, s[22:23]
	v_lshlrev_b32_e32 v146, 1, v54
	v_mov_b32_e32 v147, v5
	v_lshl_add_u64 v[14:15], v[14:15], 0, v[146:147]
	v_lshlrev_b64 v[16:17], 12, v[178:179]
	v_lshl_add_u64 v[18:19], v[14:15], 0, s[84:85]
	v_lshl_add_u64 v[16:17], s[18:19], 0, v[16:17]
	v_add_co_u32_e32 v14, vcc, s75, v14
	v_lshl_add_u64 v[16:17], v[16:17], 0, s[22:23]
	s_nop 0
	v_addc_co_u32_e32 v15, vcc, 0, v15, vcc
	v_lshl_add_u64 v[154:155], v[16:17], 0, v[146:147]
	global_load_dwordx4 v[14:17], v[14:15], off offset:1536
	v_mfma_f32_16x16x32_bf16 v[6:9], v[228:231], v[70:73], v[6:9]
	s_waitcnt vmcnt(0)
	v_mov_b32_e32 v54, v16
	s_nop 1
	v_permlane16_swap_b32_e32 v14, v54
	v_lshlrev_b32_e32 v16, 16, v14
	v_mov_b32_e32 v55, v17
	v_and_b32_e32 v17, 0xffff0000, v14
	v_mul_f32_e32 v14, 0xbfb8aa3b, v16
	v_exp_f32_e32 v14, v14
	v_permlane16_swap_b32_e32 v15, v55
	v_mfma_f32_16x16x32_bf16 v[98:101], v[248:251], v[58:61], v[66:69]
	v_add_f32_e32 v14, 1.0, v14
	v_rcp_f32_e32 v20, v14
	v_mul_f32_e32 v14, 0xbfb8aa3b, v17
	v_exp_f32_e32 v14, v14
	v_mfma_f32_16x16x32_bf16 v[10:13], v[248:251], v[70:73], v[74:77]
	global_load_dwordx4 v[78:81], v4, s[24:25]
	global_load_dwordx4 v[70:73], v4, s[24:25] offset:128
	global_load_dwordx4 v[66:69], v4, s[24:25] offset:192
	v_add_f32_e32 v14, 1.0, v14
	v_rcp_f32_e32 v21, v14
	v_lshlrev_b32_e32 v14, 16, v15
	v_and_b32_e32 v15, 0xffff0000, v15
	global_load_dwordx4 v[74:77], v4, s[24:25] offset:64
	v_pk_mul_f32 v[156:157], v[20:21], v[16:17]
	v_mul_f32_e32 v16, 0xbfb8aa3b, v14
	v_mul_f32_e32 v17, 0xbfb8aa3b, v15
	v_exp_f32_e32 v16, v16
	v_exp_f32_e32 v17, v17
	global_load_dwordx4 v[58:61], v4, s[24:25] offset:256
	v_add_f32_e32 v16, 1.0, v16
	v_add_f32_e32 v17, 1.0, v17
	v_rcp_f32_e32 v16, v16
	v_rcp_f32_e32 v17, v17
	s_nop 0
	v_pk_mul_f32 v[174:175], v[16:17], v[14:15]
	v_lshlrev_b32_e32 v14, 16, v54
	v_and_b32_e32 v15, 0xffff0000, v54
	v_mul_f32_e32 v16, 0xbfb8aa3b, v14
	v_mul_f32_e32 v17, 0xbfb8aa3b, v15
	v_exp_f32_e32 v16, v16
	v_exp_f32_e32 v17, v17
	v_add_f32_e32 v16, 1.0, v16
	v_add_f32_e32 v17, 1.0, v17
	v_rcp_f32_e32 v16, v16
	v_rcp_f32_e32 v17, v17
	s_nop 0
	v_pk_mul_f32 v[180:181], v[16:17], v[14:15]
	v_lshlrev_b32_e32 v14, 16, v55
	v_and_b32_e32 v15, 0xffff0000, v55
	v_mul_f32_e32 v16, 0xbfb8aa3b, v14
	v_mul_f32_e32 v17, 0xbfb8aa3b, v15
	v_exp_f32_e32 v16, v16
	v_exp_f32_e32 v17, v17
	v_add_f32_e32 v16, 1.0, v16
	v_add_f32_e32 v17, 1.0, v17
	v_rcp_f32_e32 v16, v16
	v_rcp_f32_e32 v17, v17
	s_nop 0
	v_pk_mul_f32 v[184:185], v[16:17], v[14:15]
	global_load_dwordx4 v[14:17], v[18:19], off offset:64
	s_waitcnt vmcnt(0)
	v_mov_b32_e32 v54, v16
	s_nop 1
	v_permlane16_swap_b32_e32 v14, v54
	v_lshlrev_b32_e32 v16, 16, v14
	v_mov_b32_e32 v55, v17
	v_and_b32_e32 v17, 0xffff0000, v14
	v_mul_f32_e32 v14, 0xbfb8aa3b, v16
	v_exp_f32_e32 v14, v14
	v_permlane16_swap_b32_e32 v15, v55
	v_add_f32_e32 v14, 1.0, v14
	v_rcp_f32_e32 v20, v14
	v_mul_f32_e32 v14, 0xbfb8aa3b, v17
	v_exp_f32_e32 v14, v14
	s_nop 0
	v_add_f32_e32 v14, 1.0, v14
	v_rcp_f32_e32 v21, v14
	v_lshlrev_b32_e32 v14, 16, v15
	v_and_b32_e32 v15, 0xffff0000, v15
	v_pk_mul_f32 v[186:187], v[20:21], v[16:17]
	v_mul_f32_e32 v16, 0xbfb8aa3b, v14
	v_mul_f32_e32 v17, 0xbfb8aa3b, v15
	v_exp_f32_e32 v16, v16
	v_exp_f32_e32 v17, v17
	v_add_f32_e32 v16, 1.0, v16
	v_add_f32_e32 v17, 1.0, v17
	v_rcp_f32_e32 v16, v16
	v_rcp_f32_e32 v17, v17
	s_nop 0
	v_pk_mul_f32 v[188:189], v[16:17], v[14:15]
	v_lshlrev_b32_e32 v14, 16, v54
	v_and_b32_e32 v15, 0xffff0000, v54
	v_mul_f32_e32 v16, 0xbfb8aa3b, v14
	v_mul_f32_e32 v17, 0xbfb8aa3b, v15
	v_exp_f32_e32 v16, v16
	v_exp_f32_e32 v17, v17
	v_add_f32_e32 v16, 1.0, v16
	v_add_f32_e32 v17, 1.0, v17
	v_rcp_f32_e32 v16, v16
	v_rcp_f32_e32 v17, v17
	s_nop 0
	v_pk_mul_f32 v[190:191], v[16:17], v[14:15]
	v_lshlrev_b32_e32 v14, 16, v55
	v_and_b32_e32 v15, 0xffff0000, v55
	v_mul_f32_e32 v16, 0xbfb8aa3b, v14
	v_mul_f32_e32 v17, 0xbfb8aa3b, v15
	v_exp_f32_e32 v16, v16
	v_exp_f32_e32 v17, v17
	global_load_dwordx4 v[54:57], v4, s[24:25] offset:320
	v_add_f32_e32 v16, 1.0, v16
	v_add_f32_e32 v17, 1.0, v17
	v_rcp_f32_e32 v16, v16
	v_rcp_f32_e32 v17, v17
	s_nop 0
	v_pk_mul_f32 v[192:193], v[16:17], v[14:15]
	global_load_dwordx4 v[14:17], v[18:19], off offset:128
	s_waitcnt vmcnt(0)
	v_mov_b32_e32 v198, v16
	s_nop 1
	v_permlane16_swap_b32_e32 v14, v198
	v_lshlrev_b32_e32 v16, 16, v14
	v_mov_b32_e32 v200, v17
	v_and_b32_e32 v17, 0xffff0000, v14
	v_mul_f32_e32 v14, 0xbfb8aa3b, v16
	v_exp_f32_e32 v14, v14
	v_permlane16_swap_b32_e32 v15, v200
	v_add_f32_e32 v14, 1.0, v14
	v_rcp_f32_e32 v20, v14
	v_mul_f32_e32 v14, 0xbfb8aa3b, v17
	v_exp_f32_e32 v14, v14
	s_nop 0
	v_add_f32_e32 v14, 1.0, v14
	v_rcp_f32_e32 v21, v14
	v_lshlrev_b32_e32 v14, 16, v15
	v_and_b32_e32 v15, 0xffff0000, v15
	v_pk_mul_f32 v[194:195], v[20:21], v[16:17]
	v_mul_f32_e32 v16, 0xbfb8aa3b, v14
	v_mul_f32_e32 v17, 0xbfb8aa3b, v15
	v_exp_f32_e32 v16, v16
	v_exp_f32_e32 v17, v17
	v_add_f32_e32 v16, 1.0, v16
	v_add_f32_e32 v17, 1.0, v17
	v_rcp_f32_e32 v16, v16
	v_rcp_f32_e32 v17, v17
	s_nop 0
	v_pk_mul_f32 v[196:197], v[16:17], v[14:15]
	v_lshlrev_b32_e32 v14, 16, v198
	v_and_b32_e32 v15, 0xffff0000, v198
	v_mul_f32_e32 v16, 0xbfb8aa3b, v14
	v_mul_f32_e32 v17, 0xbfb8aa3b, v15
	v_exp_f32_e32 v16, v16
	v_exp_f32_e32 v17, v17
	v_add_f32_e32 v16, 1.0, v16
	v_add_f32_e32 v17, 1.0, v17
	v_rcp_f32_e32 v16, v16
	v_rcp_f32_e32 v17, v17
	s_nop 0
	v_pk_mul_f32 v[198:199], v[16:17], v[14:15]
	v_lshlrev_b32_e32 v14, 16, v200
	v_and_b32_e32 v15, 0xffff0000, v200
	v_mul_f32_e32 v16, 0xbfb8aa3b, v14
	v_mul_f32_e32 v17, 0xbfb8aa3b, v15
	v_exp_f32_e32 v16, v16
	v_exp_f32_e32 v17, v17
	v_add_f32_e32 v16, 1.0, v16
	v_add_f32_e32 v17, 1.0, v17
	v_rcp_f32_e32 v16, v16
	v_rcp_f32_e32 v17, v17
	s_nop 0
	v_pk_mul_f32 v[200:201], v[16:17], v[14:15]
	global_load_dwordx4 v[14:17], v[18:19], off offset:192
	s_waitcnt vmcnt(0)
	v_mov_b32_e32 v207, v16
	s_nop 1
	v_permlane16_swap_b32_e32 v14, v207
	v_lshlrev_b32_e32 v16, 16, v14
	v_mov_b32_e32 v212, v17
	v_and_b32_e32 v17, 0xffff0000, v14
	v_mul_f32_e32 v14, 0xbfb8aa3b, v16
	v_exp_f32_e32 v14, v14
	v_permlane16_swap_b32_e32 v15, v212
	v_lshlrev_b32_e32 v206, 16, v207
	v_add_f32_e32 v14, 1.0, v14
	v_rcp_f32_e32 v202, v14
	v_mul_f32_e32 v14, 0xbfb8aa3b, v17
	v_exp_f32_e32 v14, v14
	global_load_dwordx4 v[18:21], v4, s[24:25] offset:384
	v_and_b32_e32 v207, 0xffff0000, v207
	v_add_f32_e32 v14, 1.0, v14
	v_rcp_f32_e32 v203, v14
	v_lshlrev_b32_e32 v14, 16, v15
	v_and_b32_e32 v15, 0xffff0000, v15
	v_pk_mul_f32 v[202:203], v[202:203], v[16:17]
	v_mul_f32_e32 v16, 0xbfb8aa3b, v14
	v_mul_f32_e32 v17, 0xbfb8aa3b, v15
	v_exp_f32_e32 v16, v16
	v_exp_f32_e32 v17, v17
	v_add_f32_e32 v16, 1.0, v16
	v_add_f32_e32 v17, 1.0, v17
	v_rcp_f32_e32 v16, v16
	v_rcp_f32_e32 v17, v17
	s_nop 0
	v_pk_mul_f32 v[204:205], v[16:17], v[14:15]
	global_load_dwordx4 v[14:17], v4, s[24:25] offset:448
	v_mul_f32_e32 v4, 0xbfb8aa3b, v206
	v_exp_f32_e32 v4, v4
	s_nop 0
	v_add_f32_e32 v4, 1.0, v4
	v_rcp_f32_e32 v208, v4
	v_mul_f32_e32 v4, 0xbfb8aa3b, v207
	v_exp_f32_e32 v4, v4
	s_nop 0
	v_add_f32_e32 v4, 1.0, v4
	v_rcp_f32_e32 v209, v4
	s_nop 0
	v_pk_mul_f32 v[206:207], v[208:209], v[206:207]
	v_lshlrev_b32_e32 v208, 16, v212
	v_mul_f32_e32 v4, 0xbfb8aa3b, v208
	v_exp_f32_e32 v4, v4
	v_and_b32_e32 v209, 0xffff0000, v212
	v_add_f32_e32 v4, 1.0, v4
	v_rcp_f32_e32 v212, v4
	v_mul_f32_e32 v4, 0xbfb8aa3b, v209
	v_exp_f32_e32 v4, v4
	s_nop 0
	v_add_f32_e32 v4, 1.0, v4
	v_rcp_f32_e32 v213, v4
	v_mul_f32_e32 v4, v118, v118
	v_pk_mul_f32 v[208:209], v[212:213], v[208:209]
	v_mov_b32_e32 v212, v102
	v_mov_b32_e32 v213, v106
	v_pk_fma_f32 v[212:213], v[212:213], v[212:213], v[214:215]
	v_mov_b32_e32 v214, v104
	v_mov_b32_e32 v215, v108
	v_pk_fma_f32 v[214:215], v[214:215], v[214:215], v[216:217]
	v_pk_mul_f32 v[216:217], v[110:111], v[110:111]
	v_pk_add_f32 v[212:213], v[212:213], v[214:215]
	v_pk_mul_f32 v[214:215], v[112:113], v[112:113]
	v_pk_add_f32 v[212:213], v[212:213], v[212:213] op_sel:[0,1] op_sel_hi:[1,0]
	v_pk_mov_b32 v[218:219], v[216:217], v[214:215] op_sel:[1,0]
	v_mov_b32_e32 v217, v215
	v_pk_add_f32 v[214:215], v[218:219], v[216:217]
	v_mul_f32_e32 v216, v119, v119
	v_pk_add_f32 v[214:215], v[214:215], v[214:215] op_sel:[0,1] op_sel_hi:[1,0]
	v_mov_b32_e32 v213, v4
	v_mov_b32_e32 v215, v216
	v_mul_f32_e32 v4, v115, v115
	v_mul_f32_e32 v217, v120, v120
	v_pk_add_f32 v[212:213], v[212:213], v[214:215]
	v_pk_fma_f32 v[214:215], v[114:115], v[114:115], v[4:5] op_sel_hi:[1,1,0]
	v_mul_f32_e32 v4, v117, v117
	v_mul_f32_e32 v218, v121, v121
	v_mov_b32_e32 v215, v217
	v_pk_fma_f32 v[216:217], v[116:117], v[116:117], v[4:5] op_sel_hi:[1,1,0]
	v_mul_f32_e32 v4, v130, v130
	v_mov_b32_e32 v217, v218
	v_pk_add_f32 v[214:215], v[214:215], v[216:217]
	v_pk_mul_f32 v[216:217], v[122:123], v[122:123]
	v_pk_add_f32 v[212:213], v[212:213], v[214:215]
	v_pk_mul_f32 v[214:215], v[124:125], v[124:125]
	v_pk_add_f32 v[212:213], v[212:213], v[212:213] op_sel:[0,1] op_sel_hi:[1,0]
	v_pk_mov_b32 v[218:219], v[216:217], v[214:215] op_sel:[1,0]
	v_mov_b32_e32 v217, v215
	v_pk_add_f32 v[214:215], v[218:219], v[216:217]
	v_mul_f32_e32 v216, v131, v131
	v_pk_add_f32 v[214:215], v[214:215], v[214:215] op_sel:[0,1] op_sel_hi:[1,0]
	v_mov_b32_e32 v213, v4
	v_mov_b32_e32 v215, v216
	v_mul_f32_e32 v4, v127, v127
	v_mul_f32_e32 v217, v132, v132
	v_pk_add_f32 v[212:213], v[212:213], v[214:215]
	v_pk_fma_f32 v[214:215], v[126:127], v[126:127], v[4:5] op_sel_hi:[1,1,0]
	v_mul_f32_e32 v4, v129, v129
	v_mul_f32_e32 v218, v133, v133
	v_mov_b32_e32 v215, v217
	v_pk_fma_f32 v[216:217], v[128:129], v[128:129], v[4:5] op_sel_hi:[1,1,0]
	s_nop 0
	v_mov_b32_e32 v217, v218
	v_pk_add_f32 v[214:215], v[214:215], v[216:217]
	s_nop 0
	v_pk_add_f32 v[212:213], v[212:213], v[214:215]
	v_mov_b32_e32 v215, v148
	v_mov_b32_e32 v214, v212
	v_mov_b32_e32 v148, v213
	v_pk_add_f32 v[148:149], v[214:215], v[148:149]
	ds_bpermute_b32 v213, v176, v149
	ds_bpermute_b32 v212, v176, v148
	s_waitcnt lgkmcnt(0)
	v_pk_add_f32 v[148:149], v[148:149], v[212:213]
	ds_bpermute_b32 v213, v177, v149
	ds_bpermute_b32 v212, v177, v148
	s_waitcnt lgkmcnt(0)
	v_pk_add_f32 v[212:213], v[148:149], v[212:213]
	v_mov_b64_e32 v[148:149], s[80:81]
	v_pk_fma_f32 v[212:213], v[212:213], s[68:69], v[148:149] op_sel_hi:[1,0,0]
	s_nop 0
	v_mul_f32_e32 v4, 0x4b800000, v213
	v_cmp_gt_f32_e64 s[4:5], s92, v213
	v_cmp_gt_f32_e32 vcc, s92, v212
	s_nop 0
	v_cndmask_b32_e64 v4, v213, v4, s[4:5]
	v_rsq_f32_e32 v4, v4
	s_nop 0
	v_mul_f32_e32 v213, 0x45800000, v4
	v_cndmask_b32_e64 v4, v4, v213, s[4:5]
	v_pk_mul_f32 v[134:135], v[134:135], v[4:5] op_sel_hi:[1,0]
	v_pk_mul_f32 v[136:137], v[136:137], v[4:5] op_sel_hi:[1,0]
	v_pk_mul_f32 v[134:135], v[78:79], v[134:135]
	v_pk_mul_f32 v[136:137], v[80:81], v[136:137]
	v_pk_mul_f32 v[134:135], v[156:157], v[134:135]
	v_pk_mul_f32 v[136:137], v[136:137], v[174:175]
	v_cvt_pk_bf16_f32 v134, v134, v135
	v_cvt_pk_bf16_f32 v135, v136, v137
	v_pk_mul_f32 v[136:137], v[138:139], v[4:5] op_sel_hi:[1,0]
	v_pk_mul_f32 v[138:139], v[140:141], v[4:5] op_sel_hi:[1,0]
	v_pk_mul_f32 v[136:137], v[74:75], v[136:137]
	v_pk_mul_f32 v[138:139], v[76:77], v[138:139]
	v_pk_mul_f32 v[136:137], v[180:181], v[136:137]
	v_pk_mul_f32 v[138:139], v[138:139], v[184:185]
	v_cvt_pk_bf16_f32 v136, v136, v137
	v_cvt_pk_bf16_f32 v137, v138, v139
	s_nop 0
	v_permlane16_swap_b32_e32 v134, v136
	v_permlane16_swap_b32_e32 v135, v137
	global_store_dwordx4 v[154:155], v[134:137], off offset:2560
	v_pk_mul_f32 v[138:139], v[160:161], v[4:5] op_sel_hi:[1,0]
	s_nop 0
	v_pk_mul_f32 v[134:135], v[150:151], v[4:5] op_sel_hi:[1,0]
	v_pk_mul_f32 v[136:137], v[152:153], v[4:5] op_sel_hi:[1,0]
	v_pk_mul_f32 v[134:135], v[134:135], v[70:71]
	v_pk_mul_f32 v[136:137], v[136:137], v[72:73]
	v_pk_mul_f32 v[134:135], v[134:135], v[186:187]
	v_pk_mul_f32 v[136:137], v[136:137], v[188:189]
	v_cvt_pk_bf16_f32 v134, v134, v135
	v_cvt_pk_bf16_f32 v135, v136, v137
	v_pk_mul_f32 v[136:137], v[158:159], v[4:5] op_sel_hi:[1,0]
	v_pk_mul_f32 v[138:139], v[138:139], v[68:69]
	v_pk_mul_f32 v[136:137], v[136:137], v[66:67]
	v_pk_mul_f32 v[138:139], v[138:139], v[192:193]
	v_pk_mul_f32 v[136:137], v[136:137], v[190:191]
	s_nop 0
	v_cvt_pk_bf16_f32 v136, v136, v137
	v_cvt_pk_bf16_f32 v137, v138, v139
	s_nop 0
	v_permlane16_swap_b32_e32 v134, v136
	v_permlane16_swap_b32_e32 v135, v137
	global_store_dwordx4 v[154:155], v[134:137], off offset:2624
	v_pk_mul_f32 v[138:139], v[168:169], v[4:5] op_sel_hi:[1,0]
	s_nop 0
	v_pk_mul_f32 v[134:135], v[162:163], v[4:5] op_sel_hi:[1,0]
	v_pk_mul_f32 v[136:137], v[164:165], v[4:5] op_sel_hi:[1,0]
	v_pk_mul_f32 v[134:135], v[134:135], v[58:59]
	v_pk_mul_f32 v[136:137], v[136:137], v[60:61]
	v_pk_mul_f32 v[134:135], v[134:135], v[194:195]
	v_pk_mul_f32 v[136:137], v[136:137], v[196:197]
	v_cvt_pk_bf16_f32 v134, v134, v135
	v_cvt_pk_bf16_f32 v135, v136, v137
	v_pk_mul_f32 v[136:137], v[166:167], v[4:5] op_sel_hi:[1,0]
	v_pk_mul_f32 v[138:139], v[138:139], v[56:57]
	v_pk_mul_f32 v[136:137], v[136:137], v[54:55]
	v_pk_mul_f32 v[138:139], v[138:139], v[200:201]
	v_pk_mul_f32 v[136:137], v[136:137], v[198:199]
	s_nop 0
	v_cvt_pk_bf16_f32 v136, v136, v137
	v_cvt_pk_bf16_f32 v137, v138, v139
	s_nop 0
	v_permlane16_swap_b32_e32 v134, v136
	v_permlane16_swap_b32_e32 v135, v137
	global_store_dwordx4 v[154:155], v[134:137], off offset:2688
	v_pk_mul_f32 v[138:139], v[144:145], v[4:5] op_sel_hi:[1,0]
	s_nop 0
	v_pk_mul_f32 v[134:135], v[170:171], v[4:5] op_sel_hi:[1,0]
	v_pk_mul_f32 v[136:137], v[172:173], v[4:5] op_sel_hi:[1,0]
	s_waitcnt vmcnt(4)
	v_pk_mul_f32 v[134:135], v[134:135], v[18:19]
	v_pk_mul_f32 v[136:137], v[136:137], v[20:21]
	v_pk_mul_f32 v[134:135], v[134:135], v[202:203]
	v_pk_mul_f32 v[136:137], v[136:137], v[204:205]
	v_cvt_pk_bf16_f32 v134, v134, v135
	v_cvt_pk_bf16_f32 v135, v136, v137
	v_pk_mul_f32 v[136:137], v[142:143], v[4:5] op_sel_hi:[1,0]
	v_mul_f32_e32 v4, 0x4b800000, v212
	v_cndmask_b32_e32 v4, v212, v4, vcc
	s_waitcnt vmcnt(3)
	v_pk_mul_f32 v[136:137], v[136:137], v[14:15]
	v_pk_mul_f32 v[138:139], v[138:139], v[16:17]
	v_rsq_f32_e32 v4, v4
	v_pk_mul_f32 v[136:137], v[136:137], v[206:207]
	v_pk_mul_f32 v[138:139], v[138:139], v[208:209]
	v_cvt_pk_bf16_f32 v136, v136, v137
	v_cvt_pk_bf16_f32 v137, v138, v139
	s_nop 0
	v_permlane16_swap_b32_e32 v134, v136
	v_permlane16_swap_b32_e32 v135, v137
	global_store_dwordx4 v[154:155], v[134:137], off offset:2752
	s_nop 1
	v_mul_f32_e32 v134, 0x45800000, v4
	v_cndmask_b32_e32 v4, v4, v134, vcc
	v_or_b32_e32 v134, 16, v178
	v_mad_u64_u32 v[136:137], s[4:5], v134, s2, v[2:3]
	v_mad_i32_i24 v137, s21, v243, v137
	v_lshl_add_u64 v[136:137], v[136:137], 0, s[22:23]
	v_lshl_add_u64 v[136:137], v[136:137], 0, v[146:147]
	v_lshl_add_u64 v[140:141], v[136:137], 0, s[84:85]
	v_add_co_u32_e32 v136, vcc, s75, v136
	v_pk_mul_f32 v[102:103], v[102:103], v[4:5] op_sel_hi:[1,0]
	s_nop 0
	v_addc_co_u32_e32 v137, vcc, 0, v137, vcc
	global_load_dwordx4 v[136:139], v[136:137], off offset:1536
	v_pk_mul_f32 v[102:103], v[78:79], v[102:103]
	v_pk_mul_f32 v[104:105], v[104:105], v[4:5] op_sel_hi:[1,0]
	v_pk_mul_f32 v[106:107], v[106:107], v[4:5] op_sel_hi:[1,0]
	v_pk_mul_f32 v[104:105], v[80:81], v[104:105]
	v_pk_mul_f32 v[106:107], v[74:75], v[106:107]
	v_mov_b32_e32 v135, s21
	v_pk_mul_f32 v[108:109], v[108:109], v[4:5] op_sel_hi:[1,0]
	v_lshlrev_b64 v[134:135], 12, v[134:135]
	v_pk_mul_f32 v[108:109], v[76:77], v[108:109]
	v_lshl_add_u64 v[134:135], s[18:19], 0, v[134:135]
	v_lshl_add_u64 v[134:135], v[134:135], 0, s[22:23]
	v_lshl_add_u64 v[134:135], v[134:135], 0, v[146:147]
	v_or_b32_e32 v178, 32, v178
	s_waitcnt vmcnt(0)
	v_mov_b32_e32 v144, v138
	s_nop 1
	v_permlane16_swap_b32_e32 v136, v144
	v_lshlrev_b32_e32 v138, 16, v136
	v_mov_b32_e32 v145, v139
	v_and_b32_e32 v139, 0xffff0000, v136
	v_mul_f32_e32 v136, 0xbfb8aa3b, v138
	v_exp_f32_e32 v136, v136
	v_permlane16_swap_b32_e32 v137, v145
	v_add_f32_e32 v136, 1.0, v136
	v_rcp_f32_e32 v142, v136
	v_mul_f32_e32 v136, 0xbfb8aa3b, v139
	v_exp_f32_e32 v136, v136
	s_nop 0
	v_add_f32_e32 v136, 1.0, v136
	v_rcp_f32_e32 v143, v136
	v_lshlrev_b32_e32 v136, 16, v137
	v_and_b32_e32 v137, 0xffff0000, v137
	v_pk_mul_f32 v[138:139], v[142:143], v[138:139]
	s_nop 0
	v_pk_mul_f32 v[102:103], v[138:139], v[102:103]
	v_mov_b32_e32 v142, v25
	v_cvt_pk_bf16_f32 v102, v102, v103
	v_mul_f32_e32 v103, 0xbfb8aa3b, v136
	v_exp_f32_e32 v103, v103
	v_mov_b32_e32 v143, v29
	v_pk_mul_f32 v[142:143], v[142:143], v[142:143]
	v_add_f32_e32 v103, 1.0, v103
	v_rcp_f32_e32 v138, v103
	v_mul_f32_e32 v103, 0xbfb8aa3b, v137
	v_exp_f32_e32 v103, v103
	s_nop 0
	v_add_f32_e32 v103, 1.0, v103
	v_rcp_f32_e32 v139, v103
	s_nop 0
	v_pk_mul_f32 v[136:137], v[138:139], v[136:137]
	s_nop 0
	v_pk_mul_f32 v[104:105], v[104:105], v[136:137]
	s_nop 0
	v_cvt_pk_bf16_f32 v103, v104, v105
	v_lshlrev_b32_e32 v104, 16, v144
	v_and_b32_e32 v105, 0xffff0000, v144
	v_mul_f32_e32 v136, 0xbfb8aa3b, v104
	v_mul_f32_e32 v137, 0xbfb8aa3b, v105
	v_exp_f32_e32 v136, v136
	v_exp_f32_e32 v137, v137
	v_add_f32_e32 v136, 1.0, v136
	v_add_f32_e32 v137, 1.0, v137
	v_rcp_f32_e32 v136, v136
	v_rcp_f32_e32 v137, v137
	s_nop 0
	v_pk_mul_f32 v[104:105], v[136:137], v[104:105]
	s_nop 0
	v_pk_mul_f32 v[104:105], v[104:105], v[106:107]
	v_lshlrev_b32_e32 v106, 16, v145
	v_cvt_pk_bf16_f32 v104, v104, v105
	v_mul_f32_e32 v105, 0xbfb8aa3b, v106
	v_exp_f32_e32 v105, v105
	v_and_b32_e32 v107, 0xffff0000, v145
	v_permlane16_swap_b32_e32 v102, v104
	v_add_f32_e32 v105, 1.0, v105
	v_rcp_f32_e32 v136, v105
	v_mul_f32_e32 v105, 0xbfb8aa3b, v107
	v_exp_f32_e32 v105, v105
	s_nop 0
	v_add_f32_e32 v105, 1.0, v105
	v_rcp_f32_e32 v137, v105
	s_nop 0
	v_pk_mul_f32 v[106:107], v[136:137], v[106:107]
	s_nop 0
	v_pk_mul_f32 v[106:107], v[108:109], v[106:107]
	v_pk_mul_f32 v[108:109], v[110:111], v[4:5] op_sel_hi:[1,0]
	v_cvt_pk_bf16_f32 v105, v106, v107
	s_nop 1
	v_permlane16_swap_b32_e32 v103, v105
	global_store_dwordx4 v[134:135], v[102:105], off offset:2560
	global_load_dwordx4 v[102:105], v[140:141], off offset:64
	v_pk_mul_f32 v[108:109], v[70:71], v[108:109]
	v_pk_mul_f32 v[110:111], v[116:117], v[4:5] op_sel_hi:[1,0]
	s_waitcnt vmcnt(0)
	v_mov_b32_e32 v136, v104
	s_nop 1
	v_permlane16_swap_b32_e32 v102, v136
	v_lshlrev_b32_e32 v104, 16, v102
	v_mov_b32_e32 v137, v105
	v_and_b32_e32 v105, 0xffff0000, v102
	v_mul_f32_e32 v102, 0xbfb8aa3b, v104
	v_exp_f32_e32 v102, v102
	v_permlane16_swap_b32_e32 v103, v137
	v_pk_mul_f32 v[110:111], v[68:69], v[110:111]
	v_add_f32_e32 v102, 1.0, v102
	v_rcp_f32_e32 v106, v102
	v_mul_f32_e32 v102, 0xbfb8aa3b, v105
	v_exp_f32_e32 v102, v102
	s_nop 0
	v_add_f32_e32 v102, 1.0, v102
	v_rcp_f32_e32 v107, v102
	s_nop 0
	v_pk_mul_f32 v[104:105], v[106:107], v[104:105]
	s_nop 0
	v_pk_mul_f32 v[104:105], v[108:109], v[104:105]
	v_pk_mul_f32 v[108:109], v[112:113], v[4:5] op_sel_hi:[1,0]
	v_cvt_pk_bf16_f32 v102, v104, v105
	v_lshlrev_b32_e32 v104, 16, v103
	v_and_b32_e32 v105, 0xffff0000, v103
	v_mul_f32_e32 v103, 0xbfb8aa3b, v104
	v_exp_f32_e32 v103, v103
	v_pk_mul_f32 v[108:109], v[72:73], v[108:109]
	v_add_f32_e32 v103, 1.0, v103
	v_rcp_f32_e32 v106, v103
	v_mul_f32_e32 v103, 0xbfb8aa3b, v105
	v_exp_f32_e32 v103, v103
	s_nop 0
	v_add_f32_e32 v103, 1.0, v103
	v_rcp_f32_e32 v107, v103
	s_nop 0
	v_pk_mul_f32 v[104:105], v[106:107], v[104:105]
	s_nop 0
	v_pk_mul_f32 v[104:105], v[108:109], v[104:105]
	v_pk_mul_f32 v[108:109], v[114:115], v[4:5] op_sel_hi:[1,0]
	v_cvt_pk_bf16_f32 v103, v104, v105
	v_lshlrev_b32_e32 v104, 16, v136
	v_and_b32_e32 v105, 0xffff0000, v136
	v_mul_f32_e32 v106, 0xbfb8aa3b, v104
	v_mul_f32_e32 v107, 0xbfb8aa3b, v105
	v_exp_f32_e32 v106, v106
	v_exp_f32_e32 v107, v107
	v_pk_mul_f32 v[108:109], v[66:67], v[108:109]
	v_add_f32_e32 v106, 1.0, v106
	v_add_f32_e32 v107, 1.0, v107
	v_rcp_f32_e32 v106, v106
	v_rcp_f32_e32 v107, v107
	s_nop 0
	v_pk_mul_f32 v[104:105], v[106:107], v[104:105]
	s_nop 0
	v_pk_mul_f32 v[104:105], v[108:109], v[104:105]
	v_lshlrev_b32_e32 v106, 16, v137
	v_cvt_pk_bf16_f32 v104, v104, v105
	v_mul_f32_e32 v105, 0xbfb8aa3b, v106
	v_exp_f32_e32 v105, v105
	v_and_b32_e32 v107, 0xffff0000, v137
	v_permlane16_swap_b32_e32 v102, v104
	v_add_f32_e32 v105, 1.0, v105
	v_rcp_f32_e32 v108, v105
	v_mul_f32_e32 v105, 0xbfb8aa3b, v107
	v_exp_f32_e32 v105, v105
	s_nop 0
	v_add_f32_e32 v105, 1.0, v105
	v_rcp_f32_e32 v109, v105
	s_nop 0
	v_pk_mul_f32 v[106:107], v[108:109], v[106:107]
	s_nop 0
	v_pk_mul_f32 v[106:107], v[110:111], v[106:107]
	v_pk_mul_f32 v[108:109], v[118:119], v[4:5] op_sel_hi:[1,0]
	v_cvt_pk_bf16_f32 v105, v106, v107
	s_nop 1
	v_permlane16_swap_b32_e32 v103, v105
	global_store_dwordx4 v[134:135], v[102:105], off offset:2624
	global_load_dwordx4 v[102:105], v[140:141], off offset:128
	v_pk_mul_f32 v[108:109], v[58:59], v[108:109]
	s_waitcnt vmcnt(0)
	v_mov_b32_e32 v110, v104
	s_nop 1
	v_permlane16_swap_b32_e32 v102, v110
	v_lshlrev_b32_e32 v104, 16, v102
	v_mov_b32_e32 v111, v105
	v_and_b32_e32 v105, 0xffff0000, v102
	v_mul_f32_e32 v102, 0xbfb8aa3b, v104
	v_exp_f32_e32 v102, v102
	v_permlane16_swap_b32_e32 v103, v111
	v_add_f32_e32 v102, 1.0, v102
	v_rcp_f32_e32 v106, v102
	v_mul_f32_e32 v102, 0xbfb8aa3b, v105
	v_exp_f32_e32 v102, v102
	s_nop 0
	v_add_f32_e32 v102, 1.0, v102
	v_rcp_f32_e32 v107, v102
	s_nop 0
	v_pk_mul_f32 v[104:105], v[106:107], v[104:105]
	s_nop 0
	v_pk_mul_f32 v[104:105], v[108:109], v[104:105]
	v_pk_mul_f32 v[108:109], v[120:121], v[4:5] op_sel_hi:[1,0]
	v_cvt_pk_bf16_f32 v102, v104, v105
	v_lshlrev_b32_e32 v104, 16, v103
	v_and_b32_e32 v105, 0xffff0000, v103
	v_mul_f32_e32 v103, 0xbfb8aa3b, v104
	v_exp_f32_e32 v103, v103
	v_pk_mul_f32 v[108:109], v[60:61], v[108:109]
	v_add_f32_e32 v103, 1.0, v103
	v_rcp_f32_e32 v106, v103
	v_mul_f32_e32 v103, 0xbfb8aa3b, v105
	v_exp_f32_e32 v103, v103
	s_nop 0
	v_add_f32_e32 v103, 1.0, v103
	v_rcp_f32_e32 v107, v103
	s_nop 0
	v_pk_mul_f32 v[104:105], v[106:107], v[104:105]
	s_nop 0
	v_pk_mul_f32 v[104:105], v[108:109], v[104:105]
	v_pk_mul_f32 v[108:109], v[122:123], v[4:5] op_sel_hi:[1,0]
	v_cvt_pk_bf16_f32 v103, v104, v105
	v_lshlrev_b32_e32 v104, 16, v110
	v_and_b32_e32 v105, 0xffff0000, v110
	v_mul_f32_e32 v106, 0xbfb8aa3b, v104
	v_mul_f32_e32 v107, 0xbfb8aa3b, v105
	v_exp_f32_e32 v106, v106
	v_exp_f32_e32 v107, v107
	v_pk_mul_f32 v[108:109], v[54:55], v[108:109]
	v_add_f32_e32 v106, 1.0, v106
	v_add_f32_e32 v107, 1.0, v107
	v_rcp_f32_e32 v106, v106
	v_rcp_f32_e32 v107, v107
	s_nop 0
	v_pk_mul_f32 v[104:105], v[106:107], v[104:105]
	s_nop 0
	v_pk_mul_f32 v[104:105], v[108:109], v[104:105]
	v_lshlrev_b32_e32 v106, 16, v111
	v_cvt_pk_bf16_f32 v104, v104, v105
	v_mul_f32_e32 v105, 0xbfb8aa3b, v106
	v_exp_f32_e32 v105, v105
	v_and_b32_e32 v107, 0xffff0000, v111
	v_pk_mul_f32 v[110:111], v[124:125], v[4:5] op_sel_hi:[1,0]
	v_permlane16_swap_b32_e32 v102, v104
	v_add_f32_e32 v105, 1.0, v105
	v_rcp_f32_e32 v108, v105
	v_mul_f32_e32 v105, 0xbfb8aa3b, v107
	v_exp_f32_e32 v105, v105
	v_pk_mul_f32 v[110:111], v[56:57], v[110:111]
	v_add_f32_e32 v105, 1.0, v105
	v_rcp_f32_e32 v109, v105
	s_nop 0
	v_pk_mul_f32 v[106:107], v[108:109], v[106:107]
	s_nop 0
	v_pk_mul_f32 v[106:107], v[110:111], v[106:107]
	v_pk_mul_f32 v[108:109], v[126:127], v[4:5] op_sel_hi:[1,0]
	v_cvt_pk_bf16_f32 v105, v106, v107
	s_nop 1
	v_permlane16_swap_b32_e32 v103, v105
	global_store_dwordx4 v[134:135], v[102:105], off offset:2688
	global_load_dwordx4 v[102:105], v[140:141], off offset:192
	v_pk_mul_f32 v[108:109], v[18:19], v[108:109]
	v_mov_b32_e32 v140, v23
	v_mov_b32_e32 v141, v27
	v_pk_mul_f32 v[140:141], v[140:141], v[140:141]
	s_waitcnt vmcnt(0)
	v_mov_b32_e32 v110, v104
	s_nop 1
	v_permlane16_swap_b32_e32 v102, v110
	v_lshlrev_b32_e32 v104, 16, v102
	v_mov_b32_e32 v111, v105
	v_and_b32_e32 v105, 0xffff0000, v102
	v_mul_f32_e32 v102, 0xbfb8aa3b, v104
	v_exp_f32_e32 v102, v102
	v_permlane16_swap_b32_e32 v103, v111
	v_add_f32_e32 v102, 1.0, v102
	v_rcp_f32_e32 v106, v102
	v_mul_f32_e32 v102, 0xbfb8aa3b, v105
	v_exp_f32_e32 v102, v102
	s_nop 0
	v_add_f32_e32 v102, 1.0, v102
	v_rcp_f32_e32 v107, v102
	s_nop 0
	v_pk_mul_f32 v[104:105], v[106:107], v[104:105]
	s_nop 0
	v_pk_mul_f32 v[104:105], v[108:109], v[104:105]
	v_pk_mul_f32 v[108:109], v[128:129], v[4:5] op_sel_hi:[1,0]
	v_cvt_pk_bf16_f32 v102, v104, v105
	v_lshlrev_b32_e32 v104, 16, v103
	v_and_b32_e32 v105, 0xffff0000, v103
	v_mul_f32_e32 v103, 0xbfb8aa3b, v104
	v_exp_f32_e32 v103, v103
	v_pk_mul_f32 v[108:109], v[20:21], v[108:109]
	v_add_f32_e32 v103, 1.0, v103
	v_rcp_f32_e32 v106, v103
	v_mul_f32_e32 v103, 0xbfb8aa3b, v105
	v_exp_f32_e32 v103, v103
	s_nop 0
	v_add_f32_e32 v103, 1.0, v103
	v_rcp_f32_e32 v107, v103
	s_nop 0
	v_pk_mul_f32 v[104:105], v[106:107], v[104:105]
	s_nop 0
	v_pk_mul_f32 v[104:105], v[108:109], v[104:105]
	v_pk_mul_f32 v[108:109], v[130:131], v[4:5] op_sel_hi:[1,0]
	v_cvt_pk_bf16_f32 v103, v104, v105
	v_lshlrev_b32_e32 v104, 16, v110
	v_and_b32_e32 v105, 0xffff0000, v110
	v_mul_f32_e32 v106, 0xbfb8aa3b, v104
	v_mul_f32_e32 v107, 0xbfb8aa3b, v105
	v_exp_f32_e32 v106, v106
	v_exp_f32_e32 v107, v107
	v_pk_mul_f32 v[108:109], v[14:15], v[108:109]
	v_add_f32_e32 v106, 1.0, v106
	v_add_f32_e32 v107, 1.0, v107
	v_rcp_f32_e32 v106, v106
	v_rcp_f32_e32 v107, v107
	s_nop 0
	v_pk_mul_f32 v[104:105], v[106:107], v[104:105]
	s_nop 0
	v_pk_mul_f32 v[104:105], v[108:109], v[104:105]
	v_lshlrev_b32_e32 v106, 16, v111
	v_and_b32_e32 v107, 0xffff0000, v111
	v_cvt_pk_bf16_f32 v104, v104, v105
	v_mul_f32_e32 v105, 0xbfb8aa3b, v106
	v_pk_mul_f32 v[110:111], v[132:133], v[4:5] op_sel_hi:[1,0]
	v_mul_f32_e32 v4, 0xbfb8aa3b, v107
	v_exp_f32_e32 v105, v105
	v_exp_f32_e32 v4, v4
	v_pk_mul_f32 v[110:111], v[16:17], v[110:111]
	v_permlane16_swap_b32_e32 v102, v104
	v_add_f32_e32 v105, 1.0, v105
	v_add_f32_e32 v4, 1.0, v4
	v_rcp_f32_e32 v108, v105
	v_rcp_f32_e32 v109, v4
	v_mul_f32_e32 v4, v86, v86
	v_pk_mul_f32 v[106:107], v[108:109], v[106:107]
	s_nop 0
	v_pk_mul_f32 v[106:107], v[110:111], v[106:107]
	s_nop 0
	v_cvt_pk_bf16_f32 v105, v106, v107
	s_nop 1
	v_permlane16_swap_b32_e32 v103, v105
	global_store_dwordx4 v[134:135], v[102:105], off offset:2752
	v_mov_b32_e32 v106, v49
	v_mov_b32_e32 v107, v53
	v_mov_b32_e32 v104, v47
	v_mov_b32_e32 v105, v51
	v_mov_b32_e32 v102, v46
	v_mov_b32_e32 v103, v50
	v_pk_mul_f32 v[104:105], v[104:105], v[104:105]
	v_pk_mul_f32 v[106:107], v[106:107], v[106:107]
	v_pk_fma_f32 v[102:103], v[102:103], v[102:103], v[104:105]
	v_mov_b32_e32 v104, v48
	v_mov_b32_e32 v105, v52
	v_pk_fma_f32 v[104:105], v[104:105], v[104:105], v[106:107]
	v_pk_mul_f32 v[106:107], v[62:63], v[62:63]
	v_pk_add_f32 v[102:103], v[102:103], v[104:105]
	v_pk_mul_f32 v[104:105], v[64:65], v[64:65]
	v_pk_add_f32 v[102:103], v[102:103], v[102:103] op_sel:[0,1] op_sel_hi:[1,0]
	v_pk_mov_b32 v[108:109], v[106:107], v[104:105] op_sel:[1,0]
	v_mov_b32_e32 v107, v105
	v_pk_add_f32 v[104:105], v[108:109], v[106:107]
	v_mul_f32_e32 v106, v87, v87
	v_pk_add_f32 v[104:105], v[104:105], v[104:105] op_sel:[0,1] op_sel_hi:[1,0]
	v_mov_b32_e32 v103, v4
	v_mov_b32_e32 v105, v106
	v_mul_f32_e32 v4, v83, v83
	v_mul_f32_e32 v107, v88, v88
	v_pk_add_f32 v[102:103], v[102:103], v[104:105]
	v_pk_fma_f32 v[104:105], v[82:83], v[82:83], v[4:5] op_sel_hi:[1,1,0]
	v_mul_f32_e32 v4, v85, v85
	v_mul_f32_e32 v108, v89, v89
	v_mov_b32_e32 v105, v107
	v_pk_fma_f32 v[106:107], v[84:85], v[84:85], v[4:5] op_sel_hi:[1,1,0]
	v_mul_f32_e32 v4, v98, v98
	v_mov_b32_e32 v107, v108
	v_pk_add_f32 v[104:105], v[104:105], v[106:107]
	v_pk_mul_f32 v[106:107], v[90:91], v[90:91]
	v_pk_add_f32 v[102:103], v[102:103], v[104:105]
	v_pk_mul_f32 v[104:105], v[92:93], v[92:93]
	v_pk_add_f32 v[102:103], v[102:103], v[102:103] op_sel:[0,1] op_sel_hi:[1,0]
	v_pk_mov_b32 v[108:109], v[106:107], v[104:105] op_sel:[1,0]
	v_mov_b32_e32 v107, v105
	v_pk_add_f32 v[104:105], v[108:109], v[106:107]
	v_mul_f32_e32 v106, v99, v99
	v_pk_add_f32 v[104:105], v[104:105], v[104:105] op_sel:[0,1] op_sel_hi:[1,0]
	v_mov_b32_e32 v103, v4
	v_mov_b32_e32 v105, v106
	v_mul_f32_e32 v4, v95, v95
	v_mul_f32_e32 v107, v100, v100
	v_pk_add_f32 v[102:103], v[102:103], v[104:105]
	v_pk_fma_f32 v[104:105], v[94:95], v[94:95], v[4:5] op_sel_hi:[1,1,0]
	v_mul_f32_e32 v4, v97, v97
	v_mul_f32_e32 v108, v101, v101
	v_mov_b32_e32 v105, v107
	v_pk_fma_f32 v[106:107], v[96:97], v[96:97], v[4:5] op_sel_hi:[1,1,0]
	s_nop 0
	v_mov_b32_e32 v107, v108
	v_pk_add_f32 v[104:105], v[104:105], v[106:107]
	s_nop 0
	v_pk_add_f32 v[102:103], v[102:103], v[104:105]
	v_mad_u64_u32 v[104:105], s[4:5], v178, s2, v[2:3]
	v_mad_i32_i24 v105, s21, v243, v105
	v_lshl_add_u64 v[104:105], v[104:105], 0, s[22:23]
	v_lshl_add_u64 v[106:107], v[104:105], 0, v[146:147]
	v_lshl_add_u64 v[116:117], v[106:107], 0, s[84:85]
	v_add_co_u32_e32 v106, vcc, s75, v106
	global_load_dwordx4 v[118:121], v[116:117], off offset:64
	s_nop 0
	v_addc_co_u32_e32 v107, vcc, 0, v107, vcc
	global_load_dwordx4 v[108:111], v[106:107], off offset:1536
	global_load_dwordx4 v[126:129], v[116:117], off offset:128
	v_lshlrev_b64 v[104:105], 12, v[178:179]
	v_lshl_add_u64 v[104:105], s[18:19], 0, v[104:105]
	v_lshl_add_u64 v[104:105], v[104:105], 0, s[22:23]
	v_lshl_add_u64 v[104:105], v[104:105], 0, v[146:147]
	v_or3_b32 v178, v183, s20, 48
	s_waitcnt vmcnt(2)
	v_mov_b32_e32 v124, v121
	s_nop 1
	v_permlane16_swap_b32_e32 v119, v124
	s_waitcnt vmcnt(1)
	v_mov_b32_e32 v4, v110
	s_nop 1
	v_permlane16_swap_b32_e32 v108, v4
	v_lshlrev_b32_e32 v106, 16, v108
	v_and_b32_e32 v107, 0xffff0000, v108
	v_mul_f32_e32 v108, 0xbfb8aa3b, v106
	v_exp_f32_e32 v108, v108
	v_mov_b32_e32 v114, v111
	s_nop 1
	v_permlane16_swap_b32_e32 v109, v114
	v_add_f32_e32 v108, 1.0, v108
	v_rcp_f32_e32 v110, v108
	v_mul_f32_e32 v108, 0xbfb8aa3b, v107
	v_exp_f32_e32 v108, v108
	s_waitcnt vmcnt(0)
	v_mov_b32_e32 v132, v129
	s_nop 1
	v_permlane16_swap_b32_e32 v127, v132
	v_add_f32_e32 v108, 1.0, v108
	v_rcp_f32_e32 v111, v108
	v_lshlrev_b32_e32 v108, 16, v109
	v_and_b32_e32 v109, 0xffff0000, v109
	v_pk_mul_f32 v[106:107], v[110:111], v[106:107]
	v_mul_f32_e32 v110, 0xbfb8aa3b, v108
	v_mul_f32_e32 v111, 0xbfb8aa3b, v109
	v_exp_f32_e32 v110, v110
	v_exp_f32_e32 v111, v111
	v_add_f32_e32 v110, 1.0, v110
	v_add_f32_e32 v111, 1.0, v111
	v_rcp_f32_e32 v110, v110
	v_rcp_f32_e32 v111, v111
	s_nop 0
	v_pk_mul_f32 v[108:109], v[110:111], v[108:109]
	v_lshlrev_b32_e32 v110, 16, v4
	v_and_b32_e32 v111, 0xffff0000, v4
	v_mul_f32_e32 v4, 0xbfb8aa3b, v110
	v_exp_f32_e32 v4, v4
	s_nop 0
	v_add_f32_e32 v4, 1.0, v4
	v_rcp_f32_e32 v112, v4
	v_mul_f32_e32 v4, 0xbfb8aa3b, v111
	v_exp_f32_e32 v4, v4
	s_nop 0
	v_add_f32_e32 v4, 1.0, v4
	v_rcp_f32_e32 v113, v4
	s_nop 0
	v_pk_mul_f32 v[110:111], v[112:113], v[110:111]
	v_lshlrev_b32_e32 v112, 16, v114
	v_mul_f32_e32 v4, 0xbfb8aa3b, v112
	v_exp_f32_e32 v4, v4
	v_and_b32_e32 v113, 0xffff0000, v114
	v_add_f32_e32 v4, 1.0, v4
	v_rcp_f32_e32 v114, v4
	v_mul_f32_e32 v4, 0xbfb8aa3b, v113
	v_exp_f32_e32 v4, v4
	s_nop 0
	v_add_f32_e32 v4, 1.0, v4
	v_rcp_f32_e32 v115, v4
	v_mov_b32_e32 v4, v120
	s_nop 1
	v_permlane16_swap_b32_e32 v118, v4
	v_pk_mul_f32 v[112:113], v[114:115], v[112:113]
	v_lshlrev_b32_e32 v114, 16, v118
	v_and_b32_e32 v115, 0xffff0000, v118
	v_mul_f32_e32 v118, 0xbfb8aa3b, v114
	v_exp_f32_e32 v118, v118
	s_nop 0
	v_add_f32_e32 v118, 1.0, v118
	v_rcp_f32_e32 v120, v118
	v_mul_f32_e32 v118, 0xbfb8aa3b, v115
	v_exp_f32_e32 v118, v118
	s_nop 0
	v_add_f32_e32 v118, 1.0, v118
	v_rcp_f32_e32 v121, v118
	v_lshlrev_b32_e32 v118, 16, v119
	v_and_b32_e32 v119, 0xffff0000, v119
	v_pk_mul_f32 v[114:115], v[120:121], v[114:115]
	v_mul_f32_e32 v120, 0xbfb8aa3b, v118
	v_mul_f32_e32 v121, 0xbfb8aa3b, v119
	v_exp_f32_e32 v120, v120
	v_exp_f32_e32 v121, v121
	v_add_f32_e32 v120, 1.0, v120
	v_add_f32_e32 v121, 1.0, v121
	v_rcp_f32_e32 v120, v120
	v_rcp_f32_e32 v121, v121
	s_nop 0
	v_pk_mul_f32 v[118:119], v[120:121], v[118:119]
	v_lshlrev_b32_e32 v120, 16, v4
	v_and_b32_e32 v121, 0xffff0000, v4
	v_mul_f32_e32 v4, 0xbfb8aa3b, v120
	v_exp_f32_e32 v4, v4
	s_nop 0
	v_add_f32_e32 v4, 1.0, v4
	v_rcp_f32_e32 v122, v4
	v_mul_f32_e32 v4, 0xbfb8aa3b, v121
	v_exp_f32_e32 v4, v4
	s_nop 0
	v_add_f32_e32 v4, 1.0, v4
	v_rcp_f32_e32 v123, v4
	s_nop 0
	v_pk_mul_f32 v[120:121], v[122:123], v[120:121]
	v_lshlrev_b32_e32 v122, 16, v124
	v_mul_f32_e32 v4, 0xbfb8aa3b, v122
	v_exp_f32_e32 v4, v4
	v_and_b32_e32 v123, 0xffff0000, v124
	v_add_f32_e32 v4, 1.0, v4
	v_rcp_f32_e32 v124, v4
	v_mul_f32_e32 v4, 0xbfb8aa3b, v123
	v_exp_f32_e32 v4, v4
	s_nop 0
	v_add_f32_e32 v4, 1.0, v4
	v_rcp_f32_e32 v125, v4
	v_mov_b32_e32 v4, v128
	s_nop 1
	v_permlane16_swap_b32_e32 v126, v4
	v_pk_mul_f32 v[122:123], v[124:125], v[122:123]
	v_lshlrev_b32_e32 v124, 16, v126
	v_and_b32_e32 v125, 0xffff0000, v126
	v_mul_f32_e32 v126, 0xbfb8aa3b, v124
	v_exp_f32_e32 v126, v126
	s_nop 0
	v_add_f32_e32 v126, 1.0, v126
	v_rcp_f32_e32 v128, v126
	v_mul_f32_e32 v126, 0xbfb8aa3b, v125
	v_exp_f32_e32 v126, v126
	s_nop 0
	v_add_f32_e32 v126, 1.0, v126
	v_rcp_f32_e32 v129, v126
	v_lshlrev_b32_e32 v126, 16, v127
	v_and_b32_e32 v127, 0xffff0000, v127
	v_pk_mul_f32 v[124:125], v[128:129], v[124:125]
	v_mul_f32_e32 v128, 0xbfb8aa3b, v126
	v_mul_f32_e32 v129, 0xbfb8aa3b, v127
	v_exp_f32_e32 v128, v128
	v_exp_f32_e32 v129, v129
	v_add_f32_e32 v128, 1.0, v128
	v_add_f32_e32 v129, 1.0, v129
	v_rcp_f32_e32 v128, v128
	v_rcp_f32_e32 v129, v129
	s_nop 0
	v_pk_mul_f32 v[126:127], v[128:129], v[126:127]
	v_lshlrev_b32_e32 v128, 16, v4
	v_and_b32_e32 v129, 0xffff0000, v4
	v_mul_f32_e32 v4, 0xbfb8aa3b, v128
	v_exp_f32_e32 v4, v4
	s_nop 0
	v_add_f32_e32 v4, 1.0, v4
	v_rcp_f32_e32 v130, v4
	v_mul_f32_e32 v4, 0xbfb8aa3b, v129
	v_exp_f32_e32 v4, v4
	s_nop 0
	v_add_f32_e32 v4, 1.0, v4
	v_rcp_f32_e32 v131, v4
	s_nop 0
	v_pk_mul_f32 v[128:129], v[130:131], v[128:129]
	v_lshlrev_b32_e32 v130, 16, v132
	v_mul_f32_e32 v4, 0xbfb8aa3b, v130
	v_exp_f32_e32 v4, v4
	v_and_b32_e32 v131, 0xffff0000, v132
	v_add_f32_e32 v4, 1.0, v4
	v_rcp_f32_e32 v132, v4
	v_mul_f32_e32 v4, 0xbfb8aa3b, v131
	v_exp_f32_e32 v4, v4
	s_nop 0
	v_add_f32_e32 v4, 1.0, v4
	v_rcp_f32_e32 v133, v4
	s_nop 0
	v_pk_mul_f32 v[130:131], v[132:133], v[130:131]
	global_load_dwordx4 v[132:135], v[116:117], off offset:192
	s_waitcnt vmcnt(0)
	v_mov_b32_e32 v4, v134
	s_nop 1
	v_permlane16_swap_b32_e32 v132, v4
	v_lshlrev_b32_e32 v116, 16, v132
	v_and_b32_e32 v117, 0xffff0000, v132
	v_mul_f32_e32 v132, 0xbfb8aa3b, v116
	v_exp_f32_e32 v132, v132
	v_mov_b32_e32 v138, v135
	s_nop 1
	v_permlane16_swap_b32_e32 v133, v138
	v_add_f32_e32 v132, 1.0, v132
	v_rcp_f32_e32 v134, v132
	v_mul_f32_e32 v132, 0xbfb8aa3b, v117
	v_exp_f32_e32 v132, v132
	s_nop 0
	v_add_f32_e32 v132, 1.0, v132
	v_rcp_f32_e32 v135, v132
	v_lshlrev_b32_e32 v132, 16, v133
	v_and_b32_e32 v133, 0xffff0000, v133
	v_pk_mul_f32 v[116:117], v[134:135], v[116:117]
	v_mul_f32_e32 v134, 0xbfb8aa3b, v132
	v_mul_f32_e32 v135, 0xbfb8aa3b, v133
	v_exp_f32_e32 v134, v134
	v_exp_f32_e32 v135, v135
	v_add_f32_e32 v134, 1.0, v134
	v_add_f32_e32 v135, 1.0, v135
	v_rcp_f32_e32 v134, v134
	v_rcp_f32_e32 v135, v135
	s_nop 0
	v_pk_mul_f32 v[132:133], v[134:135], v[132:133]
	v_lshlrev_b32_e32 v134, 16, v4
	v_and_b32_e32 v135, 0xffff0000, v4
	v_mul_f32_e32 v4, 0xbfb8aa3b, v134
	v_exp_f32_e32 v4, v4
	s_nop 0
	v_add_f32_e32 v4, 1.0, v4
	v_rcp_f32_e32 v136, v4
	v_mul_f32_e32 v4, 0xbfb8aa3b, v135
	v_exp_f32_e32 v4, v4
	s_nop 0
	v_add_f32_e32 v4, 1.0, v4
	v_rcp_f32_e32 v137, v4
	s_nop 0
	v_pk_mul_f32 v[134:135], v[136:137], v[134:135]
	v_lshlrev_b32_e32 v136, 16, v138
	v_mul_f32_e32 v4, 0xbfb8aa3b, v136
	v_exp_f32_e32 v4, v4
	v_and_b32_e32 v137, 0xffff0000, v138
	v_add_f32_e32 v4, 1.0, v4
	v_rcp_f32_e32 v138, v4
	v_mul_f32_e32 v4, 0xbfb8aa3b, v137
	v_exp_f32_e32 v4, v4
	s_nop 0
	v_add_f32_e32 v4, 1.0, v4
	v_rcp_f32_e32 v139, v4
	v_mul_f32_e32 v4, v38, v38
	v_pk_mul_f32 v[136:137], v[138:139], v[136:137]
	v_mov_b32_e32 v138, v22
	v_mov_b32_e32 v139, v26
	v_pk_fma_f32 v[138:139], v[138:139], v[138:139], v[140:141]
	v_mov_b32_e32 v140, v24
	v_mov_b32_e32 v141, v28
	v_pk_fma_f32 v[140:141], v[140:141], v[140:141], v[142:143]
	v_pk_mul_f32 v[142:143], v[30:31], v[30:31]
	v_pk_add_f32 v[138:139], v[138:139], v[140:141]
	v_pk_mul_f32 v[140:141], v[32:33], v[32:33]
	v_pk_add_f32 v[138:139], v[138:139], v[138:139] op_sel:[0,1] op_sel_hi:[1,0]
	v_pk_mov_b32 v[144:145], v[142:143], v[140:141] op_sel:[1,0]
	v_mov_b32_e32 v143, v141
	v_pk_add_f32 v[140:141], v[144:145], v[142:143]
	v_mul_f32_e32 v142, v39, v39
	v_pk_add_f32 v[140:141], v[140:141], v[140:141] op_sel:[0,1] op_sel_hi:[1,0]
	v_mov_b32_e32 v139, v4
	v_mov_b32_e32 v141, v142
	v_mul_f32_e32 v4, v35, v35
	v_mul_f32_e32 v143, v40, v40
	v_pk_add_f32 v[138:139], v[138:139], v[140:141]
	v_pk_fma_f32 v[140:141], v[34:35], v[34:35], v[4:5] op_sel_hi:[1,1,0]
	v_mul_f32_e32 v4, v37, v37
	v_mul_f32_e32 v144, v41, v41
	v_mov_b32_e32 v141, v143
	v_pk_fma_f32 v[142:143], v[36:37], v[36:37], v[4:5] op_sel_hi:[1,1,0]
	v_mul_f32_e32 v4, v10, v10
	v_mov_b32_e32 v143, v144
	v_pk_add_f32 v[140:141], v[140:141], v[142:143]
	v_pk_mul_f32 v[142:143], v[42:43], v[42:43]
	v_pk_add_f32 v[138:139], v[138:139], v[140:141]
	v_pk_mul_f32 v[140:141], v[44:45], v[44:45]
	v_pk_add_f32 v[138:139], v[138:139], v[138:139] op_sel:[0,1] op_sel_hi:[1,0]
	v_pk_mov_b32 v[144:145], v[142:143], v[140:141] op_sel:[1,0]
	v_mov_b32_e32 v143, v141
	v_pk_add_f32 v[140:141], v[144:145], v[142:143]
	v_mul_f32_e32 v142, v11, v11
	v_pk_add_f32 v[140:141], v[140:141], v[140:141] op_sel:[0,1] op_sel_hi:[1,0]
	v_mov_b32_e32 v139, v4
	v_mov_b32_e32 v141, v142
	v_mul_f32_e32 v4, v7, v7
	v_mul_f32_e32 v143, v12, v12
	v_pk_add_f32 v[138:139], v[138:139], v[140:141]
	v_pk_fma_f32 v[140:141], v[6:7], v[6:7], v[4:5] op_sel_hi:[1,1,0]
	v_mul_f32_e32 v4, v9, v9
	v_mul_f32_e32 v144, v13, v13
	v_mov_b32_e32 v141, v143
	v_pk_fma_f32 v[142:143], v[8:9], v[8:9], v[4:5] op_sel_hi:[1,1,0]
	s_nop 0
	v_mov_b32_e32 v143, v144
	v_pk_add_f32 v[140:141], v[140:141], v[142:143]
	s_nop 0
	v_pk_add_f32 v[138:139], v[138:139], v[140:141]
	v_mov_b32_e32 v141, v102
	v_mov_b32_e32 v140, v138
	v_mov_b32_e32 v102, v139
	v_pk_add_f32 v[102:103], v[140:141], v[102:103]
	ds_bpermute_b32 v139, v176, v103
	ds_bpermute_b32 v138, v176, v102
	s_waitcnt lgkmcnt(0)
	v_pk_add_f32 v[102:103], v[102:103], v[138:139]
	ds_bpermute_b32 v139, v177, v103
	ds_bpermute_b32 v138, v177, v102
	s_waitcnt lgkmcnt(0)
	v_pk_add_f32 v[102:103], v[102:103], v[138:139]
	s_nop 0
	v_pk_fma_f32 v[102:103], v[102:103], s[68:69], v[148:149] op_sel_hi:[1,0,0]
	s_nop 0
	v_mul_f32_e32 v4, 0x4b800000, v103
	v_cmp_gt_f32_e64 s[4:5], s92, v103
	v_cmp_gt_f32_e32 vcc, s92, v102
	s_nop 0
	v_cndmask_b32_e64 v4, v103, v4, s[4:5]
	v_rsq_f32_e32 v4, v4
	s_nop 0
	v_mul_f32_e32 v103, 0x45800000, v4
	v_cndmask_b32_e64 v4, v4, v103, s[4:5]
	v_pk_mul_f32 v[46:47], v[46:47], v[4:5] op_sel_hi:[1,0]
	v_pk_mul_f32 v[48:49], v[48:49], v[4:5] op_sel_hi:[1,0]
	v_pk_mul_f32 v[46:47], v[78:79], v[46:47]
	v_pk_mul_f32 v[48:49], v[80:81], v[48:49]
	v_pk_mul_f32 v[46:47], v[106:107], v[46:47]
	v_pk_mul_f32 v[48:49], v[48:49], v[108:109]
	v_cvt_pk_bf16_f32 v46, v46, v47
	v_cvt_pk_bf16_f32 v47, v48, v49
	v_pk_mul_f32 v[48:49], v[50:51], v[4:5] op_sel_hi:[1,0]
	v_pk_mul_f32 v[50:51], v[52:53], v[4:5] op_sel_hi:[1,0]
	v_pk_mul_f32 v[48:49], v[74:75], v[48:49]
	v_pk_mul_f32 v[50:51], v[76:77], v[50:51]
	v_pk_mul_f32 v[48:49], v[110:111], v[48:49]
	v_pk_mul_f32 v[50:51], v[50:51], v[112:113]
	v_cvt_pk_bf16_f32 v48, v48, v49
	v_cvt_pk_bf16_f32 v49, v50, v51
	s_nop 0
	v_permlane16_swap_b32_e32 v46, v48
	v_permlane16_swap_b32_e32 v47, v49
	global_store_dwordx4 v[104:105], v[46:49], off offset:2560
	v_pk_mul_f32 v[50:51], v[84:85], v[4:5] op_sel_hi:[1,0]
	v_mad_u64_u32 v[2:3], s[4:5], v178, s2, v[2:3]
	v_pk_mul_f32 v[46:47], v[62:63], v[4:5] op_sel_hi:[1,0]
	v_pk_mul_f32 v[48:49], v[64:65], v[4:5] op_sel_hi:[1,0]
	v_pk_mul_f32 v[46:47], v[70:71], v[46:47]
	v_pk_mul_f32 v[48:49], v[72:73], v[48:49]
	v_pk_mul_f32 v[46:47], v[46:47], v[114:115]
	v_pk_mul_f32 v[48:49], v[48:49], v[118:119]
	v_cvt_pk_bf16_f32 v46, v46, v47
	v_cvt_pk_bf16_f32 v47, v48, v49
	v_pk_mul_f32 v[48:49], v[82:83], v[4:5] op_sel_hi:[1,0]
	v_pk_mul_f32 v[50:51], v[68:69], v[50:51]
	v_pk_mul_f32 v[48:49], v[66:67], v[48:49]
	v_pk_mul_f32 v[50:51], v[50:51], v[122:123]
	v_pk_mul_f32 v[48:49], v[48:49], v[120:121]
	v_mad_i32_i24 v3, s21, v243, v3
	v_cvt_pk_bf16_f32 v48, v48, v49
	v_cvt_pk_bf16_f32 v49, v50, v51
	s_nop 0
	v_permlane16_swap_b32_e32 v46, v48
	v_permlane16_swap_b32_e32 v47, v49
	global_store_dwordx4 v[104:105], v[46:49], off offset:2624
	v_pk_mul_f32 v[50:51], v[92:93], v[4:5] op_sel_hi:[1,0]
	v_lshl_add_u64 v[2:3], v[2:3], 0, s[22:23]
	v_pk_mul_f32 v[46:47], v[86:87], v[4:5] op_sel_hi:[1,0]
	v_pk_mul_f32 v[48:49], v[88:89], v[4:5] op_sel_hi:[1,0]
	v_pk_mul_f32 v[46:47], v[58:59], v[46:47]
	v_pk_mul_f32 v[48:49], v[60:61], v[48:49]
	v_pk_mul_f32 v[46:47], v[46:47], v[124:125]
	v_pk_mul_f32 v[48:49], v[48:49], v[126:127]
	v_cvt_pk_bf16_f32 v46, v46, v47
	v_cvt_pk_bf16_f32 v47, v48, v49
	v_pk_mul_f32 v[48:49], v[90:91], v[4:5] op_sel_hi:[1,0]
	v_pk_mul_f32 v[50:51], v[56:57], v[50:51]
	v_pk_mul_f32 v[48:49], v[54:55], v[48:49]
	v_pk_mul_f32 v[50:51], v[50:51], v[130:131]
	v_pk_mul_f32 v[48:49], v[48:49], v[128:129]
	s_add_i32 s4, s30, 8
	v_cvt_pk_bf16_f32 v48, v48, v49
	v_cvt_pk_bf16_f32 v49, v50, v51
	s_nop 0
	v_permlane16_swap_b32_e32 v46, v48
	v_permlane16_swap_b32_e32 v47, v49
	global_store_dwordx4 v[104:105], v[46:49], off offset:2688
	v_pk_mul_f32 v[50:51], v[100:101], v[4:5] op_sel_hi:[1,0]
	s_cmp_gt_i32 s30, 3
	v_pk_mul_f32 v[46:47], v[94:95], v[4:5] op_sel_hi:[1,0]
	v_pk_mul_f32 v[48:49], v[96:97], v[4:5] op_sel_hi:[1,0]
	v_pk_mul_f32 v[46:47], v[18:19], v[46:47]
	v_pk_mul_f32 v[48:49], v[20:21], v[48:49]
	v_pk_mul_f32 v[46:47], v[46:47], v[116:117]
	v_pk_mul_f32 v[48:49], v[48:49], v[132:133]
	v_cvt_pk_bf16_f32 v46, v46, v47
	v_cvt_pk_bf16_f32 v47, v48, v49
	v_pk_mul_f32 v[48:49], v[98:99], v[4:5] op_sel_hi:[1,0]
	v_mul_f32_e32 v4, 0x4b800000, v102
	v_cndmask_b32_e32 v4, v102, v4, vcc
	v_pk_mul_f32 v[48:49], v[14:15], v[48:49]
	v_pk_mul_f32 v[50:51], v[16:17], v[50:51]
	v_rsq_f32_e32 v4, v4
	v_pk_mul_f32 v[48:49], v[48:49], v[134:135]
	v_pk_mul_f32 v[50:51], v[50:51], v[136:137]
	v_cvt_pk_bf16_f32 v48, v48, v49
	v_cvt_pk_bf16_f32 v49, v50, v51
	s_nop 0
	v_permlane16_swap_b32_e32 v46, v48
	v_permlane16_swap_b32_e32 v47, v49
	global_store_dwordx4 v[104:105], v[46:49], off offset:2752
	s_mov_b32 s30, s4
	s_nop 0
	v_mul_f32_e32 v46, 0x45800000, v4
	v_lshl_add_u64 v[48:49], v[2:3], 0, v[146:147]
	v_cndmask_b32_e32 v4, v4, v46, vcc
	v_lshl_add_u64 v[46:47], v[48:49], 0, s[84:85]
	v_add_co_u32_e32 v48, vcc, s75, v48
	v_pk_mul_f32 v[22:23], v[22:23], v[4:5] op_sel_hi:[1,0]
	s_nop 0
	v_addc_co_u32_e32 v49, vcc, 0, v49, vcc
	global_load_dwordx4 v[48:51], v[48:49], off offset:1536
	v_pk_mul_f32 v[22:23], v[78:79], v[22:23]
	v_pk_mul_f32 v[24:25], v[24:25], v[4:5] op_sel_hi:[1,0]
	v_pk_mul_f32 v[26:27], v[26:27], v[4:5] op_sel_hi:[1,0]
	v_pk_mul_f32 v[24:25], v[80:81], v[24:25]
	v_pk_mul_f32 v[26:27], v[74:75], v[26:27]
	v_pk_mul_f32 v[28:29], v[28:29], v[4:5] op_sel_hi:[1,0]
	v_lshlrev_b64 v[2:3], 12, v[178:179]
	v_pk_mul_f32 v[28:29], v[76:77], v[28:29]
	v_lshl_add_u64 v[2:3], s[18:19], 0, v[2:3]
	v_lshl_add_u64 v[2:3], v[2:3], 0, s[22:23]
	v_lshl_add_u64 v[2:3], v[2:3], 0, v[146:147]
	v_pk_mul_f32 v[6:7], v[6:7], v[4:5] op_sel_hi:[1,0]
	v_pk_mul_f32 v[8:9], v[8:9], v[4:5] op_sel_hi:[1,0]
	v_pk_mul_f32 v[6:7], v[18:19], v[6:7]
	v_pk_mul_f32 v[8:9], v[20:21], v[8:9]
	v_pk_mul_f32 v[10:11], v[10:11], v[4:5] op_sel_hi:[1,0]
	v_pk_mul_f32 v[12:13], v[12:13], v[4:5] op_sel_hi:[1,0]
	v_pk_mul_f32 v[10:11], v[14:15], v[10:11]
	v_pk_mul_f32 v[12:13], v[16:17], v[12:13]
	s_waitcnt vmcnt(0)
	v_mov_b32_e32 v62, v50
	s_nop 1
	v_permlane16_swap_b32_e32 v48, v62
	v_lshlrev_b32_e32 v50, 16, v48
	v_mov_b32_e32 v63, v51
	v_and_b32_e32 v51, 0xffff0000, v48
	v_mul_f32_e32 v48, 0xbfb8aa3b, v50
	v_exp_f32_e32 v48, v48
	v_permlane16_swap_b32_e32 v49, v63
	v_add_f32_e32 v48, 1.0, v48
	v_rcp_f32_e32 v52, v48
	v_mul_f32_e32 v48, 0xbfb8aa3b, v51
	v_exp_f32_e32 v48, v48
	s_nop 0
	v_add_f32_e32 v48, 1.0, v48
	v_rcp_f32_e32 v53, v48
	v_lshlrev_b32_e32 v48, 16, v49
	v_and_b32_e32 v49, 0xffff0000, v49
	v_pk_mul_f32 v[50:51], v[52:53], v[50:51]
	s_nop 0
	v_pk_mul_f32 v[22:23], v[50:51], v[22:23]
	s_nop 0
	v_cvt_pk_bf16_f32 v22, v22, v23
	v_mul_f32_e32 v23, 0xbfb8aa3b, v48
	v_exp_f32_e32 v23, v23
	s_nop 0
	v_add_f32_e32 v23, 1.0, v23
	v_rcp_f32_e32 v50, v23
	v_mul_f32_e32 v23, 0xbfb8aa3b, v49
	v_exp_f32_e32 v23, v23
	s_nop 0
	v_add_f32_e32 v23, 1.0, v23
	v_rcp_f32_e32 v51, v23
	s_nop 0
	v_pk_mul_f32 v[48:49], v[50:51], v[48:49]
	s_nop 0
	v_pk_mul_f32 v[24:25], v[24:25], v[48:49]
	s_nop 0
	v_cvt_pk_bf16_f32 v23, v24, v25
	v_lshlrev_b32_e32 v24, 16, v62
	v_and_b32_e32 v25, 0xffff0000, v62
	v_mul_f32_e32 v48, 0xbfb8aa3b, v24
	v_mul_f32_e32 v49, 0xbfb8aa3b, v25
	v_exp_f32_e32 v48, v48
	v_exp_f32_e32 v49, v49
	v_add_f32_e32 v48, 1.0, v48
	v_add_f32_e32 v49, 1.0, v49
	v_rcp_f32_e32 v48, v48
	v_rcp_f32_e32 v49, v49
	s_nop 0
	v_pk_mul_f32 v[24:25], v[48:49], v[24:25]
	s_nop 0
	v_pk_mul_f32 v[24:25], v[24:25], v[26:27]
	v_lshlrev_b32_e32 v26, 16, v63
	v_cvt_pk_bf16_f32 v24, v24, v25
	v_mul_f32_e32 v25, 0xbfb8aa3b, v26
	v_exp_f32_e32 v25, v25
	v_and_b32_e32 v27, 0xffff0000, v63
	v_permlane16_swap_b32_e32 v22, v24
	v_add_f32_e32 v25, 1.0, v25
	v_rcp_f32_e32 v48, v25
	v_mul_f32_e32 v25, 0xbfb8aa3b, v27
	v_exp_f32_e32 v25, v25
	s_nop 0
	v_add_f32_e32 v25, 1.0, v25
	v_rcp_f32_e32 v49, v25
	s_nop 0
	v_pk_mul_f32 v[26:27], v[48:49], v[26:27]
	s_nop 0
	v_pk_mul_f32 v[26:27], v[28:29], v[26:27]
	v_pk_mul_f32 v[28:29], v[30:31], v[4:5] op_sel_hi:[1,0]
	v_cvt_pk_bf16_f32 v25, v26, v27
	s_nop 1
	v_permlane16_swap_b32_e32 v23, v25
	global_store_dwordx4 v[2:3], v[22:25], off offset:2560
	global_load_dwordx4 v[22:25], v[46:47], off offset:64
	v_pk_mul_f32 v[28:29], v[70:71], v[28:29]
	v_pk_mul_f32 v[30:31], v[36:37], v[4:5] op_sel_hi:[1,0]
	s_waitcnt vmcnt(0)
	v_mov_b32_e32 v48, v24
	s_nop 1
	v_permlane16_swap_b32_e32 v22, v48
	v_lshlrev_b32_e32 v24, 16, v22
	v_mov_b32_e32 v49, v25
	v_and_b32_e32 v25, 0xffff0000, v22
	v_mul_f32_e32 v22, 0xbfb8aa3b, v24
	v_exp_f32_e32 v22, v22
	v_permlane16_swap_b32_e32 v23, v49
	v_pk_mul_f32 v[30:31], v[68:69], v[30:31]
	v_add_f32_e32 v22, 1.0, v22
	v_rcp_f32_e32 v26, v22
	v_mul_f32_e32 v22, 0xbfb8aa3b, v25
	v_exp_f32_e32 v22, v22
	s_nop 0
	v_add_f32_e32 v22, 1.0, v22
	v_rcp_f32_e32 v27, v22
	s_nop 0
	v_pk_mul_f32 v[24:25], v[26:27], v[24:25]
	s_nop 0
	v_pk_mul_f32 v[24:25], v[28:29], v[24:25]
	v_pk_mul_f32 v[28:29], v[32:33], v[4:5] op_sel_hi:[1,0]
	v_cvt_pk_bf16_f32 v22, v24, v25
	v_lshlrev_b32_e32 v24, 16, v23
	v_and_b32_e32 v25, 0xffff0000, v23
	v_mul_f32_e32 v23, 0xbfb8aa3b, v24
	v_exp_f32_e32 v23, v23
	v_pk_mul_f32 v[28:29], v[72:73], v[28:29]
	v_add_f32_e32 v23, 1.0, v23
	v_rcp_f32_e32 v26, v23
	v_mul_f32_e32 v23, 0xbfb8aa3b, v25
	v_exp_f32_e32 v23, v23
	s_nop 0
	v_add_f32_e32 v23, 1.0, v23
	v_rcp_f32_e32 v27, v23
	s_nop 0
	v_pk_mul_f32 v[24:25], v[26:27], v[24:25]
	s_nop 0
	v_pk_mul_f32 v[24:25], v[28:29], v[24:25]
	v_pk_mul_f32 v[28:29], v[34:35], v[4:5] op_sel_hi:[1,0]
	v_cvt_pk_bf16_f32 v23, v24, v25
	v_lshlrev_b32_e32 v24, 16, v48
	v_and_b32_e32 v25, 0xffff0000, v48
	v_mul_f32_e32 v26, 0xbfb8aa3b, v24
	v_mul_f32_e32 v27, 0xbfb8aa3b, v25
	v_exp_f32_e32 v26, v26
	v_exp_f32_e32 v27, v27
	v_pk_mul_f32 v[28:29], v[66:67], v[28:29]
	v_add_f32_e32 v26, 1.0, v26
	v_add_f32_e32 v27, 1.0, v27
	v_rcp_f32_e32 v26, v26
	v_rcp_f32_e32 v27, v27
	s_nop 0
	v_pk_mul_f32 v[24:25], v[26:27], v[24:25]
	s_nop 0
	v_pk_mul_f32 v[24:25], v[28:29], v[24:25]
	v_lshlrev_b32_e32 v26, 16, v49
	v_cvt_pk_bf16_f32 v24, v24, v25
	v_mul_f32_e32 v25, 0xbfb8aa3b, v26
	v_exp_f32_e32 v25, v25
	v_and_b32_e32 v27, 0xffff0000, v49
	v_permlane16_swap_b32_e32 v22, v24
	v_add_f32_e32 v25, 1.0, v25
	v_rcp_f32_e32 v28, v25
	v_mul_f32_e32 v25, 0xbfb8aa3b, v27
	v_exp_f32_e32 v25, v25
	s_nop 0
	v_add_f32_e32 v25, 1.0, v25
	v_rcp_f32_e32 v29, v25
	s_nop 0
	v_pk_mul_f32 v[26:27], v[28:29], v[26:27]
	s_nop 0
	v_pk_mul_f32 v[26:27], v[30:31], v[26:27]
	v_pk_mul_f32 v[28:29], v[38:39], v[4:5] op_sel_hi:[1,0]
	v_cvt_pk_bf16_f32 v25, v26, v27
	s_nop 1
	v_permlane16_swap_b32_e32 v23, v25
	global_store_dwordx4 v[2:3], v[22:25], off offset:2624
	global_load_dwordx4 v[22:25], v[46:47], off offset:128
	v_pk_mul_f32 v[28:29], v[58:59], v[28:29]
	s_waitcnt vmcnt(0)
	v_mov_b32_e32 v30, v24
	s_nop 1
	v_permlane16_swap_b32_e32 v22, v30
	v_lshlrev_b32_e32 v24, 16, v22
	v_mov_b32_e32 v31, v25
	v_and_b32_e32 v25, 0xffff0000, v22
	v_mul_f32_e32 v22, 0xbfb8aa3b, v24
	v_exp_f32_e32 v22, v22
	v_permlane16_swap_b32_e32 v23, v31
	v_add_f32_e32 v22, 1.0, v22
	v_rcp_f32_e32 v26, v22
	v_mul_f32_e32 v22, 0xbfb8aa3b, v25
	v_exp_f32_e32 v22, v22
	s_nop 0
	v_add_f32_e32 v22, 1.0, v22
	v_rcp_f32_e32 v27, v22
	s_nop 0
	v_pk_mul_f32 v[24:25], v[26:27], v[24:25]
	s_nop 0
	v_pk_mul_f32 v[24:25], v[28:29], v[24:25]
	v_pk_mul_f32 v[28:29], v[40:41], v[4:5] op_sel_hi:[1,0]
	v_cvt_pk_bf16_f32 v22, v24, v25
	v_lshlrev_b32_e32 v24, 16, v23
	v_and_b32_e32 v25, 0xffff0000, v23
	v_mul_f32_e32 v23, 0xbfb8aa3b, v24
	v_exp_f32_e32 v23, v23
	v_pk_mul_f32 v[28:29], v[60:61], v[28:29]
	v_add_f32_e32 v23, 1.0, v23
	v_rcp_f32_e32 v26, v23
	v_mul_f32_e32 v23, 0xbfb8aa3b, v25
	v_exp_f32_e32 v23, v23
	s_nop 0
	v_add_f32_e32 v23, 1.0, v23
	v_rcp_f32_e32 v27, v23
	s_nop 0
	v_pk_mul_f32 v[24:25], v[26:27], v[24:25]
	s_nop 0
	v_pk_mul_f32 v[24:25], v[28:29], v[24:25]
	v_pk_mul_f32 v[28:29], v[42:43], v[4:5] op_sel_hi:[1,0]
	v_cvt_pk_bf16_f32 v23, v24, v25
	v_lshlrev_b32_e32 v24, 16, v30
	v_and_b32_e32 v25, 0xffff0000, v30
	v_mul_f32_e32 v26, 0xbfb8aa3b, v24
	v_mul_f32_e32 v27, 0xbfb8aa3b, v25
	v_exp_f32_e32 v26, v26
	v_exp_f32_e32 v27, v27
	v_pk_mul_f32 v[28:29], v[54:55], v[28:29]
	v_add_f32_e32 v26, 1.0, v26
	v_add_f32_e32 v27, 1.0, v27
	v_rcp_f32_e32 v26, v26
	v_rcp_f32_e32 v27, v27
	s_nop 0
	v_pk_mul_f32 v[24:25], v[26:27], v[24:25]
	s_nop 0
	v_pk_mul_f32 v[24:25], v[28:29], v[24:25]
	v_lshlrev_b32_e32 v26, 16, v31
	v_cvt_pk_bf16_f32 v24, v24, v25
	v_mul_f32_e32 v25, 0xbfb8aa3b, v26
	v_exp_f32_e32 v25, v25
	v_and_b32_e32 v27, 0xffff0000, v31
	v_pk_mul_f32 v[30:31], v[44:45], v[4:5] op_sel_hi:[1,0]
	v_permlane16_swap_b32_e32 v22, v24
	v_add_f32_e32 v25, 1.0, v25
	v_rcp_f32_e32 v28, v25
	v_mul_f32_e32 v25, 0xbfb8aa3b, v27
	v_exp_f32_e32 v25, v25
	v_pk_mul_f32 v[30:31], v[56:57], v[30:31]
	v_add_f32_e32 v25, 1.0, v25
	v_rcp_f32_e32 v29, v25
	s_nop 0
	v_pk_mul_f32 v[26:27], v[28:29], v[26:27]
	s_nop 0
	v_pk_mul_f32 v[26:27], v[30:31], v[26:27]
	s_nop 0
	v_cvt_pk_bf16_f32 v25, v26, v27
	global_load_dwordx4 v[26:29], v[46:47], off offset:192
	s_nop 0
	v_permlane16_swap_b32_e32 v23, v25
	global_store_dwordx4 v[2:3], v[22:25], off offset:2688
	s_waitcnt vmcnt(1)
	s_nop 0
	v_mov_b32_e32 v25, v28
	s_nop 1
	v_permlane16_swap_b32_e32 v26, v25
	v_lshlrev_b32_e32 v22, 16, v26
	v_and_b32_e32 v23, 0xffff0000, v26
	v_mul_f32_e32 v26, 0xbfb8aa3b, v22
	v_mul_f32_e32 v18, 0xbfb8aa3b, v23
	v_exp_f32_e32 v26, v26
	v_exp_f32_e32 v18, v18
	v_mov_b32_e32 v24, v29
	s_nop 1
	v_permlane16_swap_b32_e32 v27, v24
	v_add_f32_e32 v26, 1.0, v26
	v_add_f32_e32 v18, 1.0, v18
	v_rcp_f32_e32 v28, v26
	v_rcp_f32_e32 v29, v18
	s_nop 0
	v_pk_mul_f32 v[18:19], v[28:29], v[22:23]
	s_nop 0
	v_pk_mul_f32 v[6:7], v[6:7], v[18:19]
	v_lshlrev_b32_e32 v18, 16, v27
	v_cvt_pk_bf16_f32 v6, v6, v7
	v_mul_f32_e32 v7, 0xbfb8aa3b, v18
	v_exp_f32_e32 v7, v7
	v_and_b32_e32 v19, 0xffff0000, v27
	v_add_f32_e32 v7, 1.0, v7
	v_rcp_f32_e32 v22, v7
	v_mul_f32_e32 v7, 0xbfb8aa3b, v19
	v_exp_f32_e32 v7, v7
	s_nop 0
	v_add_f32_e32 v7, 1.0, v7
	v_rcp_f32_e32 v23, v7
	s_nop 0
	v_pk_mul_f32 v[18:19], v[22:23], v[18:19]
	s_nop 0
	v_pk_mul_f32 v[8:9], v[8:9], v[18:19]
	s_nop 0
	v_cvt_pk_bf16_f32 v7, v8, v9
	v_lshlrev_b32_e32 v8, 16, v25
	v_and_b32_e32 v9, 0xffff0000, v25
	v_mul_f32_e32 v18, 0xbfb8aa3b, v8
	v_mul_f32_e32 v14, 0xbfb8aa3b, v9
	v_exp_f32_e32 v18, v18
	v_exp_f32_e32 v14, v14
	v_add_f32_e32 v18, 1.0, v18
	v_add_f32_e32 v14, 1.0, v14
	v_rcp_f32_e32 v18, v18
	v_rcp_f32_e32 v19, v14
	s_nop 0
	v_pk_mul_f32 v[8:9], v[18:19], v[8:9]
	s_nop 0
	v_pk_mul_f32 v[8:9], v[10:11], v[8:9]
	v_lshlrev_b32_e32 v10, 16, v24
	v_and_b32_e32 v11, 0xffff0000, v24
	v_cvt_pk_bf16_f32 v8, v8, v9
	v_mul_f32_e32 v9, 0xbfb8aa3b, v10
	v_mul_f32_e32 v4, 0xbfb8aa3b, v11
	v_exp_f32_e32 v9, v9
	v_exp_f32_e32 v4, v4
	v_permlane16_swap_b32_e32 v6, v8
	v_add_f32_e32 v9, 1.0, v9
	v_add_f32_e32 v4, 1.0, v4
	v_rcp_f32_e32 v14, v9
	v_rcp_f32_e32 v15, v4
	s_nop 0
	v_pk_mul_f32 v[10:11], v[14:15], v[10:11]
	s_nop 0
	v_pk_mul_f32 v[10:11], v[12:13], v[10:11]
	s_nop 0
	v_cvt_pk_bf16_f32 v9, v10, v11
	s_nop 1
	v_permlane16_swap_b32_e32 v7, v9
	global_store_dwordx4 v[2:3], v[6:9], off offset:2752
	s_waitcnt lgkmcnt(0)
	s_cbranch_scc0 .LBB0_426
	s_branch .LBB0_423

.LBB0_429:
	s_add_u32 s24, s10, 0xc0000
	s_addc_u32 s25, s11, 0
	s_add_u32 s26, s10, 0x180000
	s_addc_u32 s27, s11, 0
	s_add_u32 s28, s8, 0x3000000
	s_addc_u32 s29, s9, 0
	s_add_u32 s30, s8, 0x6000000
	s_addc_u32 s31, s9, 0
	s_add_u32 s32, s6, 0x47400000
	s_addc_u32 s33, s7, 0
	s_mul_i32 s36, s88, 23
	v_add_u32_e32 v198, s36, v2
	s_movk_i32 s36, 8
	v_mul_hi_u32 v192, v2, s18
	v_lshrrev_b32_e32 v193, 4, v192
	v_mul_u32_u24_e32 v192, 0x60, v193
	v_sub_u32_e32 v194, v2, v192
	v_lshrrev_b32_e32 v195, 4, v194
	v_mul_u32_u24_e32 v192, 24, v193
	v_lshl_add_u32 v196, v195, 2, v192
	v_mul_u32_u24_e32 v192, 0x600, v193
	v_lshl_add_u32 v197, v194, 4, v192
	v_lshlrev_b32_e32 v192, 12, v193
	v_lshl_add_u32 v133, v194, 4, v192
	global_load_dword v130, v196, s[10:11]
	global_load_dword v131, v196, s[24:25]
	global_load_dword v132, v196, s[26:27]
	global_load_dwordx4 v[134:137], v197, s[8:9]
	global_load_dwordx4 v[138:141], v197, s[28:29]
	global_load_dwordx4 v[142:145], v197, s[30:31]
	v_add_u32_e32 v199, s88, v2
	v_mul_hi_u32 v192, v199, s18
	v_lshrrev_b32_e32 v193, 4, v192
	v_mul_u32_u24_e32 v192, 0x60, v193
	v_sub_u32_e32 v194, v199, v192
	v_lshrrev_b32_e32 v195, 4, v194
	v_mul_u32_u24_e32 v192, 24, v193
	v_lshl_add_u32 v196, v195, 2, v192
	v_mul_u32_u24_e32 v192, 0x600, v193
	v_lshl_add_u32 v197, v194, 4, v192
	v_lshlrev_b32_e32 v192, 12, v193
	v_lshl_add_u32 v153, v194, 4, v192
	global_load_dword v150, v196, s[10:11]
	global_load_dword v151, v196, s[24:25]
	global_load_dword v152, v196, s[26:27]
	global_load_dwordx4 v[154:157], v197, s[8:9]
	global_load_dwordx4 v[158:161], v197, s[28:29]
	global_load_dwordx4 v[162:165], v197, s[30:31]
	v_add_u32_e32 v199, s88, v199
.Lmerge_loop:
	v_mul_hi_u32 v192, v199, s18
	v_lshrrev_b32_e32 v193, 4, v192
	v_mul_u32_u24_e32 v192, 0x60, v193
	v_sub_u32_e32 v194, v199, v192
	v_lshrrev_b32_e32 v195, 4, v194
	v_mul_u32_u24_e32 v192, 24, v193
	v_lshl_add_u32 v196, v195, 2, v192
	v_mul_u32_u24_e32 v192, 0x600, v193
	v_lshl_add_u32 v197, v194, 4, v192
	v_lshlrev_b32_e32 v192, 12, v193
	v_lshl_add_u32 v173, v194, 4, v192
	global_load_dword v170, v196, s[10:11]
	global_load_dword v171, v196, s[24:25]
	global_load_dword v172, v196, s[26:27]
	global_load_dwordx4 v[174:177], v197, s[8:9]
	global_load_dwordx4 v[178:181], v197, s[28:29]
	global_load_dwordx4 v[182:185], v197, s[30:31]
	v_add_u32_e32 v199, s88, v199
	v_min_u32_e32 v199, v199, v198
	s_waitcnt vmcnt(12)
	v_max3_f32 v200, v130, v131, v132
	v_sub_f32_e32 v130, v130, v200
	v_mul_f32_e32 v130, 0x3fb8aa3b, v130
	v_exp_f32_e32 v207, v130
	v_sub_f32_e32 v130, v131, v200
	v_mul_f32_e32 v130, 0x3fb8aa3b, v130
	v_exp_f32_e32 v206, v130
	v_sub_f32_e32 v130, v132, v200
	v_mul_f32_e32 v130, 0x3fb8aa3b, v130
	v_exp_f32_e32 v130, v130
	v_add_f32_e32 v132, v207, v206
	v_add_f32_e32 v132, v130, v132
	v_div_scale_f32 v200, s[38:39], v132, v132, 1.0
	v_rcp_f32_e32 v131, v200
	s_nop 0
	v_fma_f32 v202, -v200, v131, 1.0
	v_fmac_f32_e32 v131, v202, v131
	v_div_scale_f32 v202, vcc, 1.0, v132, 1.0
	v_mul_f32_e32 v203, v202, v131
	v_fma_f32 v204, -v200, v203, v202
	v_fmac_f32_e32 v203, v204, v131
	v_fma_f32 v200, -v200, v203, v202
	v_div_fmas_f32 v200, v200, v131, v203
	v_div_fixup_f32 v208, v200, v132, 1.0
	v_pk_mul_f32 v[206:207], v[206:207], v[208:209] op_sel_hi:[1,0]
	v_mul_f32_e32 v212, v130, v208
	v_lshlrev_b32_e32 v224, 16, v134
	v_and_b32_e32 v223, 0xffff0000, v134
	v_lshlrev_b32_e32 v134, 16, v135
	v_and_b32_e32 v225, 0xffff0000, v138
	v_lshlrev_b32_e32 v222, 16, v138
	v_pk_mul_f32 v[224:225], v[206:207], v[224:225] op_sel:[1,0] op_sel_hi:[0,1]
	v_pk_fma_f32 v[222:223], v[206:207], v[222:223], v[224:225]
	v_and_b32_e32 v225, 0xffff0000, v135
	v_and_b32_e32 v135, 0xffff0000, v139
	v_lshlrev_b32_e32 v224, 16, v139
	v_pk_mul_f32 v[134:135], v[206:207], v[134:135] op_sel:[1,0] op_sel_hi:[0,1]
	v_lshlrev_b32_e32 v138, 16, v143
	v_and_b32_e32 v139, 0xffff0000, v143
	v_pk_fma_f32 v[134:135], v[206:207], v[224:225], v[134:135]
	v_and_b32_e32 v217, 0xffff0000, v137
	v_lshlrev_b32_e32 v218, 16, v137
	v_pk_fma_f32 v[138:139], v[212:213], v[138:139], v[134:135] op_sel_hi:[0,1,1]
	v_and_b32_e32 v135, 0xffff0000, v136
	v_lshlrev_b32_e32 v136, 16, v136
	v_and_b32_e32 v137, 0xffff0000, v140
	v_lshlrev_b32_e32 v134, 16, v140
	v_pk_mul_f32 v[136:137], v[206:207], v[136:137] op_sel:[1,0] op_sel_hi:[0,1]
	v_lshlrev_b32_e32 v216, 16, v141
	v_and_b32_e32 v219, 0xffff0000, v141
	v_lshlrev_b32_e32 v140, 16, v144
	v_and_b32_e32 v141, 0xffff0000, v144
	v_pk_fma_f32 v[134:135], v[206:207], v[134:135], v[136:137]
	v_lshlrev_b32_e32 v220, 16, v145
	v_pk_fma_f32 v[136:137], v[212:213], v[140:141], v[134:135] op_sel_hi:[0,1,1]
	v_pk_mul_f32 v[134:135], v[206:207], v[218:219] op_sel:[1,0] op_sel_hi:[0,1]
	v_and_b32_e32 v221, 0xffff0000, v145
	v_lshlrev_b32_e32 v226, 16, v142
	v_and_b32_e32 v227, 0xffff0000, v142
	v_pk_fma_f32 v[134:135], v[206:207], v[216:217], v[134:135]
	v_pk_fma_f32 v[222:223], v[212:213], v[226:227], v[222:223] op_sel_hi:[0,1,1]
	v_pk_fma_f32 v[140:141], v[212:213], v[220:221], v[134:135] op_sel_hi:[0,1,1]
	v_cvt_pk_bf16_f32 v134, v222, v223
	v_cvt_pk_bf16_f32 v135, v138, v139
	v_cvt_pk_bf16_f32 v136, v136, v137
	v_cvt_pk_bf16_f32 v137, v140, v141
	global_store_dwordx4 v133, v[134:137], s[32:33] offset:1024
	v_mul_hi_u32 v192, v199, s18
	v_lshrrev_b32_e32 v193, 4, v192
	v_mul_u32_u24_e32 v192, 0x60, v193
	v_sub_u32_e32 v194, v199, v192
	v_lshrrev_b32_e32 v195, 4, v194
	v_mul_u32_u24_e32 v192, 24, v193
	v_lshl_add_u32 v196, v195, 2, v192
	v_mul_u32_u24_e32 v192, 0x600, v193
	v_lshl_add_u32 v197, v194, 4, v192
	v_lshlrev_b32_e32 v192, 12, v193
	v_lshl_add_u32 v133, v194, 4, v192
	global_load_dword v130, v196, s[10:11]
	global_load_dword v131, v196, s[24:25]
	global_load_dword v132, v196, s[26:27]
	global_load_dwordx4 v[134:137], v197, s[8:9]
	global_load_dwordx4 v[138:141], v197, s[28:29]
	global_load_dwordx4 v[142:145], v197, s[30:31]
	v_add_u32_e32 v199, s88, v199
	v_min_u32_e32 v199, v199, v198
	s_waitcnt vmcnt(13)
	v_max3_f32 v200, v150, v151, v152
	v_sub_f32_e32 v150, v150, v200
	v_mul_f32_e32 v150, 0x3fb8aa3b, v150
	v_exp_f32_e32 v207, v150
	v_sub_f32_e32 v150, v151, v200
	v_mul_f32_e32 v150, 0x3fb8aa3b, v150
	v_exp_f32_e32 v206, v150
	v_sub_f32_e32 v150, v152, v200
	v_mul_f32_e32 v150, 0x3fb8aa3b, v150
	v_exp_f32_e32 v150, v150
	v_add_f32_e32 v152, v207, v206
	v_add_f32_e32 v152, v150, v152
	v_div_scale_f32 v200, s[38:39], v152, v152, 1.0
	v_rcp_f32_e32 v151, v200
	s_nop 0
	v_fma_f32 v202, -v200, v151, 1.0
	v_fmac_f32_e32 v151, v202, v151
	v_div_scale_f32 v202, vcc, 1.0, v152, 1.0
	v_mul_f32_e32 v203, v202, v151
	v_fma_f32 v204, -v200, v203, v202
	v_fmac_f32_e32 v203, v204, v151
	v_fma_f32 v200, -v200, v203, v202
	v_div_fmas_f32 v200, v200, v151, v203
	v_div_fixup_f32 v208, v200, v152, 1.0
	v_pk_mul_f32 v[206:207], v[206:207], v[208:209] op_sel_hi:[1,0]
	v_mul_f32_e32 v212, v150, v208
	v_lshlrev_b32_e32 v224, 16, v154
	v_and_b32_e32 v223, 0xffff0000, v154
	v_lshlrev_b32_e32 v154, 16, v155
	v_and_b32_e32 v225, 0xffff0000, v158
	v_lshlrev_b32_e32 v222, 16, v158
	v_pk_mul_f32 v[224:225], v[206:207], v[224:225] op_sel:[1,0] op_sel_hi:[0,1]
	v_pk_fma_f32 v[222:223], v[206:207], v[222:223], v[224:225]
	v_and_b32_e32 v225, 0xffff0000, v155
	v_and_b32_e32 v155, 0xffff0000, v159
	v_lshlrev_b32_e32 v224, 16, v159
	v_pk_mul_f32 v[154:155], v[206:207], v[154:155] op_sel:[1,0] op_sel_hi:[0,1]
	v_lshlrev_b32_e32 v158, 16, v163
	v_and_b32_e32 v159, 0xffff0000, v163
	v_pk_fma_f32 v[154:155], v[206:207], v[224:225], v[154:155]
	v_and_b32_e32 v217, 0xffff0000, v157
	v_lshlrev_b32_e32 v218, 16, v157
	v_pk_fma_f32 v[158:159], v[212:213], v[158:159], v[154:155] op_sel_hi:[0,1,1]
	v_and_b32_e32 v155, 0xffff0000, v156
	v_lshlrev_b32_e32 v156, 16, v156
	v_and_b32_e32 v157, 0xffff0000, v160
	v_lshlrev_b32_e32 v154, 16, v160
	v_pk_mul_f32 v[156:157], v[206:207], v[156:157] op_sel:[1,0] op_sel_hi:[0,1]
	v_lshlrev_b32_e32 v216, 16, v161
	v_and_b32_e32 v219, 0xffff0000, v161
	v_lshlrev_b32_e32 v160, 16, v164
	v_and_b32_e32 v161, 0xffff0000, v164
	v_pk_fma_f32 v[154:155], v[206:207], v[154:155], v[156:157]
	v_lshlrev_b32_e32 v220, 16, v165
	v_pk_fma_f32 v[156:157], v[212:213], v[160:161], v[154:155] op_sel_hi:[0,1,1]
	v_pk_mul_f32 v[154:155], v[206:207], v[218:219] op_sel:[1,0] op_sel_hi:[0,1]
	v_and_b32_e32 v221, 0xffff0000, v165
	v_lshlrev_b32_e32 v226, 16, v162
	v_and_b32_e32 v227, 0xffff0000, v162
	v_pk_fma_f32 v[154:155], v[206:207], v[216:217], v[154:155]
	v_pk_fma_f32 v[222:223], v[212:213], v[226:227], v[222:223] op_sel_hi:[0,1,1]
	v_pk_fma_f32 v[160:161], v[212:213], v[220:221], v[154:155] op_sel_hi:[0,1,1]
	v_cvt_pk_bf16_f32 v154, v222, v223
	v_cvt_pk_bf16_f32 v155, v158, v159
	v_cvt_pk_bf16_f32 v156, v156, v157
	v_cvt_pk_bf16_f32 v157, v160, v161
	global_store_dwordx4 v153, v[154:157], s[32:33] offset:1024
	v_mul_hi_u32 v192, v199, s18
	v_lshrrev_b32_e32 v193, 4, v192
	v_mul_u32_u24_e32 v192, 0x60, v193
	v_sub_u32_e32 v194, v199, v192
	v_lshrrev_b32_e32 v195, 4, v194
	v_mul_u32_u24_e32 v192, 24, v193
	v_lshl_add_u32 v196, v195, 2, v192
	v_mul_u32_u24_e32 v192, 0x600, v193
	v_lshl_add_u32 v197, v194, 4, v192
	v_lshlrev_b32_e32 v192, 12, v193
	v_lshl_add_u32 v153, v194, 4, v192
	global_load_dword v150, v196, s[10:11]
	global_load_dword v151, v196, s[24:25]
	global_load_dword v152, v196, s[26:27]
	global_load_dwordx4 v[154:157], v197, s[8:9]
	global_load_dwordx4 v[158:161], v197, s[28:29]
	global_load_dwordx4 v[162:165], v197, s[30:31]
	v_add_u32_e32 v199, s88, v199
	v_min_u32_e32 v199, v199, v198
	s_waitcnt vmcnt(14)
	v_max3_f32 v200, v170, v171, v172
	v_sub_f32_e32 v170, v170, v200
	v_mul_f32_e32 v170, 0x3fb8aa3b, v170
	v_exp_f32_e32 v207, v170
	v_sub_f32_e32 v170, v171, v200
	v_mul_f32_e32 v170, 0x3fb8aa3b, v170
	v_exp_f32_e32 v206, v170
	v_sub_f32_e32 v170, v172, v200
	v_mul_f32_e32 v170, 0x3fb8aa3b, v170
	v_exp_f32_e32 v170, v170
	v_add_f32_e32 v172, v207, v206
	v_add_f32_e32 v172, v170, v172
	v_div_scale_f32 v200, s[38:39], v172, v172, 1.0
	v_rcp_f32_e32 v171, v200
	s_nop 0
	v_fma_f32 v202, -v200, v171, 1.0
	v_fmac_f32_e32 v171, v202, v171
	v_div_scale_f32 v202, vcc, 1.0, v172, 1.0
	v_mul_f32_e32 v203, v202, v171
	v_fma_f32 v204, -v200, v203, v202
	v_fmac_f32_e32 v203, v204, v171
	v_fma_f32 v200, -v200, v203, v202
	v_div_fmas_f32 v200, v200, v171, v203
	v_div_fixup_f32 v208, v200, v172, 1.0
	v_pk_mul_f32 v[206:207], v[206:207], v[208:209] op_sel_hi:[1,0]
	v_mul_f32_e32 v212, v170, v208
	v_lshlrev_b32_e32 v224, 16, v174
	v_and_b32_e32 v223, 0xffff0000, v174
	v_lshlrev_b32_e32 v174, 16, v175
	v_and_b32_e32 v225, 0xffff0000, v178
	v_lshlrev_b32_e32 v222, 16, v178
	v_pk_mul_f32 v[224:225], v[206:207], v[224:225] op_sel:[1,0] op_sel_hi:[0,1]
	v_pk_fma_f32 v[222:223], v[206:207], v[222:223], v[224:225]
	v_and_b32_e32 v225, 0xffff0000, v175
	v_and_b32_e32 v175, 0xffff0000, v179
	v_lshlrev_b32_e32 v224, 16, v179
	v_pk_mul_f32 v[174:175], v[206:207], v[174:175] op_sel:[1,0] op_sel_hi:[0,1]
	v_lshlrev_b32_e32 v178, 16, v183
	v_and_b32_e32 v179, 0xffff0000, v183
	v_pk_fma_f32 v[174:175], v[206:207], v[224:225], v[174:175]
	v_and_b32_e32 v217, 0xffff0000, v177
	v_lshlrev_b32_e32 v218, 16, v177
	v_pk_fma_f32 v[178:179], v[212:213], v[178:179], v[174:175] op_sel_hi:[0,1,1]
	v_and_b32_e32 v175, 0xffff0000, v176
	v_lshlrev_b32_e32 v176, 16, v176
	v_and_b32_e32 v177, 0xffff0000, v180
	v_lshlrev_b32_e32 v174, 16, v180
	v_pk_mul_f32 v[176:177], v[206:207], v[176:177] op_sel:[1,0] op_sel_hi:[0,1]
	v_lshlrev_b32_e32 v216, 16, v181
	v_and_b32_e32 v219, 0xffff0000, v181
	v_lshlrev_b32_e32 v180, 16, v184
	v_and_b32_e32 v181, 0xffff0000, v184
	v_pk_fma_f32 v[174:175], v[206:207], v[174:175], v[176:177]
	v_lshlrev_b32_e32 v220, 16, v185
	v_pk_fma_f32 v[176:177], v[212:213], v[180:181], v[174:175] op_sel_hi:[0,1,1]
	v_pk_mul_f32 v[174:175], v[206:207], v[218:219] op_sel:[1,0] op_sel_hi:[0,1]
	v_and_b32_e32 v221, 0xffff0000, v185
	v_lshlrev_b32_e32 v226, 16, v182
	v_and_b32_e32 v227, 0xffff0000, v182
	v_pk_fma_f32 v[174:175], v[206:207], v[216:217], v[174:175]
	v_pk_fma_f32 v[222:223], v[212:213], v[226:227], v[222:223] op_sel_hi:[0,1,1]
	v_pk_fma_f32 v[180:181], v[212:213], v[220:221], v[174:175] op_sel_hi:[0,1,1]
	v_cvt_pk_bf16_f32 v174, v222, v223
	v_cvt_pk_bf16_f32 v175, v178, v179
	v_cvt_pk_bf16_f32 v176, v176, v177
	v_cvt_pk_bf16_f32 v177, v180, v181
	global_store_dwordx4 v173, v[174:177], s[32:33] offset:1024
	s_sub_u32 s36, s36, 1
	s_cmp_lg_u32 s36, 0
	s_cbranch_scc1 .Lmerge_loop
